# GEMM1 SwiGLU epilogue: scalar scale/add pairs fused into v_pk_mul_f32 / v_pk_add_f32
# baseline (speedup 1.0000x reference)
; #define STG(P, GB) do { const char* _gb = (GB); \
;     _Pragma("unroll") for (int _i = 0; _i < 2; ++_i) { \
;       __builtin_amdgcn_global_load_lds((const unsigned*)(_gb + voff[_i]), \
;         (LAS unsigned*)((LAS char*)(P) + ldsw + _i * 8192), 16, 0, 0); } } while (0)
; #define LDA(dst, b, h) _Pragma("unroll") for (int m = 0; m < 4; ++m) _Pragma("unroll") for (int k = 0; k < 2; ++k) \
;     dst[m][k] = *(const LAS bf16x8*)((LAS char*)SA(b, h) + aoff + m * 2048 + k * 1024)
; #define LDB(dst, b, h) _Pragma("unroll") for (int n = 0; n < 2; ++n) _Pragma("unroll") for (int k = 0; k < 2; ++k) \
;     dst[n][k] = *(const LAS bf16x8*)((LAS char*)SB(b, h) + boff + n * 2048 + k * 1024)
; #define MMA(ai, bj, At_, Bt_) do { __builtin_amdgcn_s_setprio(1); \
;     _Pragma("unroll") for (int m = 0; m < 4; ++m) _Pragma("unroll") for (int n = 0; n < 2; ++n) _Pragma("unroll") for (int k = 0; k < 2; ++k) \
;       acc[ai][bj][m][n] = __builtin_amdgcn_mfma_f32_16x16x32_bf16(Bt_[n][k], At_[m][k], acc[ai][bj][m][n], 0, 0, 0); \
;     __builtin_amdgcn_s_setprio(0); } while (0)
; #define WAIT_L(n) asm volatile("s_waitcnt lgkmcnt(" #n ")" ::: "memory")
; #define BAR __builtin_amdgcn_s_barrier()
; #define SCHED __builtin_amdgcn_sched_barrier(0)
; __device__ __forceinline__ void gemm_phase(const bf16_t* __restrict__ A, const bf16_t* __restrict__ Bt, bf16_t* __restrict__ C, int M, int N, int K,
;                                            int ldc, const int EPI, char* smem, const int wid_u) {
;     ...
;       LDB(B0, 0, 0); SCHED; LDA(At, 0, 0); STG(SA(1, 1), a1 + hstep);
;       WAIT_L(8); BAR; WAIT_L(0); MMA(0, 0, At, B0); BAR; SCHED;
;       LDB(B1, 0, 1); STG(SB(0, 0), b2);
;       BAR; WAIT_L(0); MMA(0, 1, At, B1); BAR;
;       LDA(At, 0, 1); STG(SA(0, 0), a2);
;       BAR; WAIT_L(0); MMA(1, 0, At, B0); BAR; SCHED;
.LBB0_145:
	ds_read_b128 v[150:153], v146
	ds_read_b128 v[154:157], v146 offset:1024
	ds_read_b128 v[158:161], v146 offset:2048
	ds_read_b128 v[162:165], v146 offset:3072
	s_add_u32 s18, s16, 0x100
	s_addc_u32 s19, s17, 0
	s_cmp_eq_u32 s49, 12
	s_cselect_b32 s23, s44, s19
	s_cselect_b32 s22, s45, s18
	s_cselect_b32 s21, s11, s48
	s_cselect_b32 s20, s46, s47
	v_lshl_add_u64 v[142:143], s[16:17], 0, v[136:137]
	s_add_i32 m0, s28, 0xc000
	ds_read_b128 v[166:169], v147
	ds_read_b128 v[170:173], v147 offset:1024
	ds_read_b128 v[174:177], v147 offset:2048
	ds_read_b128 v[178:181], v147 offset:3072
	ds_read_b128 v[182:185], v147 offset:4096
	ds_read_b128 v[186:189], v147 offset:5120
	ds_read_b128 v[190:193], v147 offset:6144
	ds_read_b128 v[194:197], v147 offset:7168
	global_load_lds_dwordx4 v[142:143], off
	v_lshl_add_u64 v[142:143], s[16:17], 0, v[134:135]
	s_add_i32 m0, s28, 0xe000
	s_nop 0
	global_load_lds_dwordx4 v[142:143], off
	s_waitcnt lgkmcnt(8)
	s_barrier
	s_waitcnt lgkmcnt(0)
	s_waitcnt lgkmcnt(0)
	v_mfma_f32_16x16x32_bf16 v[124:127], v[150:153], v[166:169], v[124:127]
	v_mfma_f32_16x16x32_bf16 v[120:123], v[158:161], v[166:169], v[120:123]
	v_mfma_f32_16x16x32_bf16 v[108:111], v[150:153], v[174:177], v[108:111]
	v_mfma_f32_16x16x32_bf16 v[104:107], v[158:161], v[174:177], v[104:107]
	v_mfma_f32_16x16x32_bf16 v[92:95], v[150:153], v[182:185], v[92:95]
	v_mfma_f32_16x16x32_bf16 v[88:91], v[158:161], v[182:185], v[88:91]
	v_mfma_f32_16x16x32_bf16 v[76:79], v[150:153], v[190:193], v[76:79]
	v_mfma_f32_16x16x32_bf16 v[72:75], v[158:161], v[190:193], v[72:75]
	v_mfma_f32_16x16x32_bf16 v[124:127], v[154:157], v[170:173], v[124:127]
	v_mfma_f32_16x16x32_bf16 v[120:123], v[162:165], v[170:173], v[120:123]
	v_mfma_f32_16x16x32_bf16 v[108:111], v[154:157], v[178:181], v[108:111]
	v_mfma_f32_16x16x32_bf16 v[104:107], v[162:165], v[178:181], v[104:107]
	v_mfma_f32_16x16x32_bf16 v[92:95], v[154:157], v[186:189], v[92:95]
	v_mfma_f32_16x16x32_bf16 v[88:91], v[162:165], v[186:189], v[88:91]
	v_mfma_f32_16x16x32_bf16 v[76:79], v[154:157], v[194:197], v[76:79]
	v_mfma_f32_16x16x32_bf16 v[72:75], v[162:165], v[194:197], v[72:75]
	s_barrier
	s_add_i32 s16, s36, s27
	v_lshl_add_u64 v[142:143], s[20:21], 0, v[130:131]
	s_mov_b32 m0, s16
	ds_read_b128 v[198:201], v148
	ds_read_b128 v[202:205], v148 offset:1024
	ds_read_b128 v[206:209], v148 offset:2048
	ds_read_b128 v[210:213], v148 offset:3072
	global_load_lds_dwordx4 v[142:143], off
	v_lshl_add_u64 v[214:215], s[20:21], 0, v[128:129]
	s_add_i32 m0, s16, 0x2000
	s_nop 0
	global_load_lds_dwordx4 v[214:215], off
	s_barrier
	s_waitcnt lgkmcnt(0)
	s_waitcnt lgkmcnt(0)
	v_mfma_f32_16x16x32_bf16 v[116:119], v[198:201], v[166:169], v[116:119]
	v_mfma_f32_16x16x32_bf16 v[112:115], v[206:209], v[166:169], v[112:115]
	v_mfma_f32_16x16x32_bf16 v[100:103], v[198:201], v[174:177], v[100:103]
	v_mfma_f32_16x16x32_bf16 v[96:99], v[206:209], v[174:177], v[96:99]
	v_mfma_f32_16x16x32_bf16 v[84:87], v[198:201], v[182:185], v[84:87]
	v_mfma_f32_16x16x32_bf16 v[80:83], v[206:209], v[182:185], v[80:83]
	v_mfma_f32_16x16x32_bf16 v[68:71], v[198:201], v[190:193], v[68:71]
	v_mfma_f32_16x16x32_bf16 v[64:67], v[206:209], v[190:193], v[64:67]
	v_mfma_f32_16x16x32_bf16 v[116:119], v[202:205], v[170:173], v[116:119]
	v_mfma_f32_16x16x32_bf16 v[112:115], v[210:213], v[170:173], v[112:115]
	v_mfma_f32_16x16x32_bf16 v[100:103], v[202:205], v[178:181], v[100:103]
	v_mfma_f32_16x16x32_bf16 v[96:99], v[210:213], v[178:181], v[96:99]
	v_mfma_f32_16x16x32_bf16 v[84:87], v[202:205], v[186:189], v[84:87]
	v_mfma_f32_16x16x32_bf16 v[80:83], v[210:213], v[186:189], v[80:83]
	v_mfma_f32_16x16x32_bf16 v[68:71], v[202:205], v[194:197], v[68:71]
	v_mfma_f32_16x16x32_bf16 v[64:67], v[210:213], v[194:197], v[64:67]
	s_mov_b32 m0, s28
	v_lshl_add_u64 v[216:217], s[22:23], 0, v[130:131]
	s_barrier
	ds_read_b128 v[166:169], v147 offset:16384
	ds_read_b128 v[170:173], v147 offset:17408
	ds_read_b128 v[174:177], v147 offset:18432
	ds_read_b128 v[178:181], v147 offset:19456
	ds_read_b128 v[182:185], v147 offset:20480
	ds_read_b128 v[186:189], v147 offset:21504
	ds_read_b128 v[190:193], v147 offset:22528
	ds_read_b128 v[194:197], v147 offset:23552
	global_load_lds_dwordx4 v[216:217], off
	v_lshl_add_u64 v[218:219], s[22:23], 0, v[128:129]
	s_mov_b32 m0, s29
	s_nop 0
	global_load_lds_dwordx4 v[218:219], off
	s_barrier
	s_waitcnt lgkmcnt(0)
	s_waitcnt lgkmcnt(0)
	v_mfma_f32_16x16x32_bf16 v[60:63], v[150:153], v[166:169], v[60:63]
	v_mfma_f32_16x16x32_bf16 v[56:59], v[158:161], v[166:169], v[56:59]
	v_mfma_f32_16x16x32_bf16 v[44:47], v[150:153], v[174:177], v[44:47]
	v_mfma_f32_16x16x32_bf16 v[40:43], v[158:161], v[174:177], v[40:43]
	v_mfma_f32_16x16x32_bf16 v[28:31], v[150:153], v[182:185], v[28:31]
	v_mfma_f32_16x16x32_bf16 v[24:27], v[158:161], v[182:185], v[24:27]
	v_mfma_f32_16x16x32_bf16 v[12:15], v[150:153], v[190:193], v[12:15]
	v_mfma_f32_16x16x32_bf16 v[8:11], v[158:161], v[190:193], v[8:11]
	v_mfma_f32_16x16x32_bf16 v[60:63], v[154:157], v[170:173], v[60:63]
	v_mfma_f32_16x16x32_bf16 v[56:59], v[162:165], v[170:173], v[56:59]
	v_mfma_f32_16x16x32_bf16 v[44:47], v[154:157], v[178:181], v[44:47]
	v_mfma_f32_16x16x32_bf16 v[40:43], v[162:165], v[178:181], v[40:43]
	v_mfma_f32_16x16x32_bf16 v[28:31], v[154:157], v[186:189], v[28:31]
	v_mfma_f32_16x16x32_bf16 v[24:27], v[162:165], v[186:189], v[24:27]
	v_mfma_f32_16x16x32_bf16 v[12:15], v[154:157], v[194:197], v[12:15]
	v_mfma_f32_16x16x32_bf16 v[8:11], v[162:165], v[194:197], v[8:11]
	s_barrier
; #define STG(P, GB) do { const char* _gb = (GB); \
;     _Pragma("unroll") for (int _i = 0; _i < 2; ++_i) { \
;       __builtin_amdgcn_global_load_lds((const unsigned*)(_gb + voff[_i]), \
;         (LAS unsigned*)((LAS char*)(P) + ldsw + _i * 8192), 16, 0, 0); } } while (0)
; #define LDA(dst, b, h) _Pragma("unroll") for (int m = 0; m < 4; ++m) _Pragma("unroll") for (int k = 0; k < 2; ++k) \
;     dst[m][k] = *(const LAS bf16x8*)((LAS char*)SA(b, h) + aoff + m * 2048 + k * 1024)
; #define LDB(dst, b, h) _Pragma("unroll") for (int n = 0; n < 2; ++n) _Pragma("unroll") for (int k = 0; k < 2; ++k) \
;     dst[n][k] = *(const LAS bf16x8*)((LAS char*)SB(b, h) + boff + n * 2048 + k * 1024)
; #define MMA(ai, bj, At_, Bt_) do { __builtin_amdgcn_s_setprio(1); \
;     _Pragma("unroll") for (int m = 0; m < 4; ++m) _Pragma("unroll") for (int n = 0; n < 2; ++n) _Pragma("unroll") for (int k = 0; k < 2; ++k) \
;       acc[ai][bj][m][n] = __builtin_amdgcn_mfma_f32_16x16x32_bf16(Bt_[n][k], At_[m][k], acc[ai][bj][m][n], 0, 0, 0); \
;     __builtin_amdgcn_s_setprio(0); } while (0)
; #define WAIT_V(n) asm volatile("s_waitcnt vmcnt(" #n ")" ::: "memory")
; #define WAIT_L(n) asm volatile("s_waitcnt lgkmcnt(" #n ")" ::: "memory")
; #define BAR __builtin_amdgcn_s_barrier()
; #define SCHED __builtin_amdgcn_sched_barrier(0)
; __device__ __forceinline__ void gemm_phase(const bf16_t* __restrict__ A, const bf16_t* __restrict__ Bt, bf16_t* __restrict__ C, int M, int N, int K,
;                                            int ldc, const int EPI, char* smem, const int wid_u) {
;     ...
;       STG(SB(0, 1), b2 + hstep);
;       WAIT_V(6); BAR; MMA(1, 1, At, B1); BAR;
;       LDB(B0, 1, 0); SCHED; LDA(At, 1, 0); STG(SA(0, 1), a2 + hstep);
;       WAIT_L(8); BAR; WAIT_L(0); MMA(0, 0, At, B0); BAR; SCHED;
;       LDB(B1, 1, 1); STG(SB(1, 0), b3);
;       BAR; WAIT_L(0); MMA(0, 1, At, B1); BAR;
;       LDA(At, 1, 1); STG(SA(1, 0), a3);
;       BAR; WAIT_L(0); MMA(1, 0, At, B0); BAR; SCHED;
	s_add_u32 s16, s20, 0x40000
	s_addc_u32 s17, s21, 0
	s_add_i32 s50, s37, s27
	v_lshl_add_u64 v[150:151], s[16:17], 0, v[130:131]
	s_mov_b32 m0, s50
	s_nop 0
	global_load_lds_dwordx4 v[150:151], off
	v_lshl_add_u64 v[150:151], s[16:17], 0, v[128:129]
	s_add_i32 m0, s50, 0x2000
	s_nop 0
	global_load_lds_dwordx4 v[150:151], off
	s_waitcnt vmcnt(6)
	s_barrier
	v_mfma_f32_16x16x32_bf16 v[52:55], v[198:201], v[166:169], v[52:55]
	v_mfma_f32_16x16x32_bf16 v[48:51], v[206:209], v[166:169], v[48:51]
	v_mfma_f32_16x16x32_bf16 v[36:39], v[198:201], v[174:177], v[36:39]
	v_mfma_f32_16x16x32_bf16 v[32:35], v[206:209], v[174:177], v[32:35]
	v_mfma_f32_16x16x32_bf16 v[20:23], v[198:201], v[182:185], v[20:23]
	v_mfma_f32_16x16x32_bf16 v[16:19], v[206:209], v[182:185], v[16:19]
	v_mfma_f32_16x16x32_bf16 v[4:7], v[198:201], v[190:193], v[4:7]
	v_mfma_f32_16x16x32_bf16 v[0:3], v[206:209], v[190:193], v[0:3]
	v_mfma_f32_16x16x32_bf16 v[52:55], v[202:205], v[170:173], v[52:55]
	v_mfma_f32_16x16x32_bf16 v[48:51], v[210:213], v[170:173], v[48:51]
	v_mfma_f32_16x16x32_bf16 v[36:39], v[202:205], v[178:181], v[36:39]
	v_mfma_f32_16x16x32_bf16 v[32:35], v[210:213], v[178:181], v[32:35]
	v_mfma_f32_16x16x32_bf16 v[20:23], v[202:205], v[186:189], v[20:23]
	v_mfma_f32_16x16x32_bf16 v[16:19], v[210:213], v[186:189], v[16:19]
	v_mfma_f32_16x16x32_bf16 v[4:7], v[202:205], v[194:197], v[4:7]
	v_mfma_f32_16x16x32_bf16 v[0:3], v[210:213], v[194:197], v[0:3]
	s_add_i32 s50, 0, 0x18000
	v_add_u32_e32 v149, s50, v145
	s_barrier
	ds_read_b128 v[150:153], v149
	ds_read_b128 v[154:157], v149 offset:1024
	ds_read_b128 v[158:161], v149 offset:2048
	ds_read_b128 v[162:165], v149 offset:3072
	s_add_u32 s16, s22, 0x40000
	s_addc_u32 s17, s23, 0
	s_mov_b32 m0, s30
	v_lshl_add_u64 v[198:199], s[16:17], 0, v[130:131]
	ds_read_b128 v[166:169], v147 offset:32768
	ds_read_b128 v[170:173], v147 offset:33792
	ds_read_b128 v[174:177], v147 offset:34816
	ds_read_b128 v[178:181], v147 offset:35840
	ds_read_b128 v[182:185], v147 offset:36864
	ds_read_b128 v[186:189], v147 offset:37888
	ds_read_b128 v[190:193], v147 offset:38912
	ds_read_b128 v[194:197], v147 offset:39936
	global_load_lds_dwordx4 v[198:199], off
	v_lshl_add_u64 v[198:199], s[16:17], 0, v[128:129]
	s_mov_b32 m0, s31
	s_nop 0
	global_load_lds_dwordx4 v[198:199], off
	s_waitcnt lgkmcnt(8)
	s_barrier
	s_waitcnt lgkmcnt(0)
	s_waitcnt lgkmcnt(0)
	v_mfma_f32_16x16x32_bf16 v[124:127], v[150:153], v[166:169], v[124:127]
	v_mfma_f32_16x16x32_bf16 v[120:123], v[158:161], v[166:169], v[120:123]
	v_mfma_f32_16x16x32_bf16 v[108:111], v[150:153], v[174:177], v[108:111]
	v_mfma_f32_16x16x32_bf16 v[104:107], v[158:161], v[174:177], v[104:107]
	v_mfma_f32_16x16x32_bf16 v[92:95], v[150:153], v[182:185], v[92:95]
	v_mfma_f32_16x16x32_bf16 v[88:91], v[158:161], v[182:185], v[88:91]
	v_mfma_f32_16x16x32_bf16 v[76:79], v[150:153], v[190:193], v[76:79]
	v_mfma_f32_16x16x32_bf16 v[72:75], v[158:161], v[190:193], v[72:75]
	v_mfma_f32_16x16x32_bf16 v[124:127], v[154:157], v[170:173], v[124:127]
	v_mfma_f32_16x16x32_bf16 v[120:123], v[162:165], v[170:173], v[120:123]
	v_mfma_f32_16x16x32_bf16 v[108:111], v[154:157], v[178:181], v[108:111]
	v_mfma_f32_16x16x32_bf16 v[104:107], v[162:165], v[178:181], v[104:107]
	v_mfma_f32_16x16x32_bf16 v[92:95], v[154:157], v[186:189], v[92:95]
	v_mfma_f32_16x16x32_bf16 v[88:91], v[162:165], v[186:189], v[88:91]
	v_mfma_f32_16x16x32_bf16 v[76:79], v[154:157], v[194:197], v[76:79]
	v_mfma_f32_16x16x32_bf16 v[72:75], v[162:165], v[194:197], v[72:75]
	s_barrier
	s_add_i32 s22, 0, 0x1c000
	s_add_i32 s16, s50, s27
	v_add_u32_e32 v149, s22, v145
	v_lshl_add_u64 v[142:143], v[142:143], 0, s[6:7]
	s_mov_b32 m0, s16
	ds_read_b128 v[198:201], v149
	ds_read_b128 v[202:205], v149 offset:1024
	ds_read_b128 v[206:209], v149 offset:2048
	ds_read_b128 v[210:213], v149 offset:3072
	global_load_lds_dwordx4 v[142:143], off
	v_lshl_add_u64 v[142:143], v[214:215], 0, s[6:7]
	s_add_i32 m0, s16, 0x2000
	s_nop 0
	global_load_lds_dwordx4 v[142:143], off
	s_barrier
	s_waitcnt lgkmcnt(0)
	s_waitcnt lgkmcnt(0)
	v_mfma_f32_16x16x32_bf16 v[116:119], v[198:201], v[166:169], v[116:119]
	v_mfma_f32_16x16x32_bf16 v[112:115], v[206:209], v[166:169], v[112:115]
	v_mfma_f32_16x16x32_bf16 v[100:103], v[198:201], v[174:177], v[100:103]
	v_mfma_f32_16x16x32_bf16 v[96:99], v[206:209], v[174:177], v[96:99]
	v_mfma_f32_16x16x32_bf16 v[84:87], v[198:201], v[182:185], v[84:87]
	v_mfma_f32_16x16x32_bf16 v[80:83], v[206:209], v[182:185], v[80:83]
	v_mfma_f32_16x16x32_bf16 v[68:71], v[198:201], v[190:193], v[68:71]
	v_mfma_f32_16x16x32_bf16 v[64:67], v[206:209], v[190:193], v[64:67]
	v_mfma_f32_16x16x32_bf16 v[116:119], v[202:205], v[170:173], v[116:119]
	v_mfma_f32_16x16x32_bf16 v[112:115], v[210:213], v[170:173], v[112:115]
	v_mfma_f32_16x16x32_bf16 v[100:103], v[202:205], v[178:181], v[100:103]
	v_mfma_f32_16x16x32_bf16 v[96:99], v[210:213], v[178:181], v[96:99]
	v_mfma_f32_16x16x32_bf16 v[84:87], v[202:205], v[186:189], v[84:87]
	v_mfma_f32_16x16x32_bf16 v[80:83], v[210:213], v[186:189], v[80:83]
	v_mfma_f32_16x16x32_bf16 v[68:71], v[202:205], v[194:197], v[68:71]
	v_mfma_f32_16x16x32_bf16 v[64:67], v[210:213], v[194:197], v[64:67]
	s_mov_b32 m0, s34
	v_lshl_add_u64 v[142:143], v[216:217], 0, s[6:7]
	s_barrier
	ds_read_b128 v[166:169], v147 offset:49152
	ds_read_b128 v[170:173], v147 offset:50176
	ds_read_b128 v[174:177], v147 offset:51200
	ds_read_b128 v[178:181], v147 offset:52224
	ds_read_b128 v[182:185], v147 offset:53248
	ds_read_b128 v[186:189], v147 offset:54272
	ds_read_b128 v[190:193], v147 offset:55296
	ds_read_b128 v[194:197], v147 offset:56320
	global_load_lds_dwordx4 v[142:143], off
	v_lshl_add_u64 v[142:143], v[218:219], 0, s[6:7]
	s_mov_b32 m0, s35
	s_nop 0
	global_load_lds_dwordx4 v[142:143], off
	s_barrier
; #define STG(P, GB) do { const char* _gb = (GB); \
;     _Pragma("unroll") for (int _i = 0; _i < 2; ++_i) { \
;       __builtin_amdgcn_global_load_lds((const unsigned*)(_gb + voff[_i]), \
;         (LAS unsigned*)((LAS char*)(P) + ldsw + _i * 8192), 16, 0, 0); } } while (0)
; #define LDA(dst, b, h) _Pragma("unroll") for (int m = 0; m < 4; ++m) _Pragma("unroll") for (int k = 0; k < 2; ++k) \
;     dst[m][k] = *(const LAS bf16x8*)((LAS char*)SA(b, h) + aoff + m * 2048 + k * 1024)
; #define LDB(dst, b, h) _Pragma("unroll") for (int n = 0; n < 2; ++n) _Pragma("unroll") for (int k = 0; k < 2; ++k) \
;     dst[n][k] = *(const LAS bf16x8*)((LAS char*)SB(b, h) + boff + n * 2048 + k * 1024)
; #define MMA(ai, bj, At_, Bt_) do { __builtin_amdgcn_s_setprio(1); \
;     _Pragma("unroll") for (int m = 0; m < 4; ++m) _Pragma("unroll") for (int n = 0; n < 2; ++n) _Pragma("unroll") for (int k = 0; k < 2; ++k) \
;       acc[ai][bj][m][n] = __builtin_amdgcn_mfma_f32_16x16x32_bf16(Bt_[n][k], At_[m][k], acc[ai][bj][m][n], 0, 0, 0); \
;     __builtin_amdgcn_s_setprio(0); } while (0)
; #define WAIT_V(n) asm volatile("s_waitcnt vmcnt(" #n ")" ::: "memory")
; #define WAIT_L(n) asm volatile("s_waitcnt lgkmcnt(" #n ")" ::: "memory")
; #define BAR __builtin_amdgcn_s_barrier()
; #define SCHED __builtin_amdgcn_sched_barrier(0)
; __device__ __forceinline__ void gemm_phase(const bf16_t* __restrict__ A, const bf16_t* __restrict__ Bt, bf16_t* __restrict__ C, int M, int N, int K,
;                                            int ldc, const int EPI, char* smem, const int wid_u) {
;     ...
;       LDB(B1, 1, 1); STG(SB(1, 0), b3);
;       BAR; WAIT_L(0); MMA(0, 1, At, B1); BAR;
;       LDA(At, 1, 1); STG(SA(1, 0), a3);
;       BAR; WAIT_L(0); MMA(1, 0, At, B0); BAR; SCHED;
;       STG(SB(1, 1), b3 + hstep);
;       WAIT_V(6); BAR; MMA(1, 1, At, B1); BAR;
;     ...
;             float o[8];
; #pragma unroll
;             for (int n = 0; n < 2; ++n) {
;               const f32x4 a = acc[ai][0][m][n], b = acc[ai][1][m][n];
; #pragma unroll
;               for (int j = 0; j < 4; ++j) o[n * 4 + j] = a[j] * __builtin_amdgcn_rcpf(1.f + __expf(-a[j])) * b[j];
;             }
;             *(uint4*)(C + row * ldc + (bcol >> 1) + wc * 32 + fq * 8) = pack8(o);
	s_waitcnt lgkmcnt(0)
	s_waitcnt lgkmcnt(0)
	v_mfma_f32_16x16x32_bf16 v[60:63], v[150:153], v[166:169], v[60:63]
	v_mfma_f32_16x16x32_bf16 v[56:59], v[158:161], v[166:169], v[56:59]
	v_mfma_f32_16x16x32_bf16 v[44:47], v[150:153], v[174:177], v[44:47]
	v_mfma_f32_16x16x32_bf16 v[40:43], v[158:161], v[174:177], v[40:43]
	v_mfma_f32_16x16x32_bf16 v[28:31], v[150:153], v[182:185], v[28:31]
	v_mfma_f32_16x16x32_bf16 v[24:27], v[158:161], v[182:185], v[24:27]
	v_mfma_f32_16x16x32_bf16 v[12:15], v[150:153], v[190:193], v[12:15]
	v_mfma_f32_16x16x32_bf16 v[8:11], v[158:161], v[190:193], v[8:11]
	v_mfma_f32_16x16x32_bf16 v[60:63], v[154:157], v[170:173], v[60:63]
	v_mfma_f32_16x16x32_bf16 v[56:59], v[162:165], v[170:173], v[56:59]
	v_mfma_f32_16x16x32_bf16 v[44:47], v[154:157], v[178:181], v[44:47]
	v_mfma_f32_16x16x32_bf16 v[40:43], v[162:165], v[178:181], v[40:43]
	v_mfma_f32_16x16x32_bf16 v[28:31], v[154:157], v[186:189], v[28:31]
	v_mfma_f32_16x16x32_bf16 v[24:27], v[162:165], v[186:189], v[24:27]
	v_mfma_f32_16x16x32_bf16 v[12:15], v[154:157], v[194:197], v[12:15]
	v_mfma_f32_16x16x32_bf16 v[8:11], v[162:165], v[194:197], v[8:11]
	s_barrier
	s_add_u32 s16, s20, 0x40080
	s_addc_u32 s17, s21, 0
	s_add_i32 s20, s22, s27
	v_lshl_add_u64 v[142:143], s[16:17], 0, v[130:131]
	s_mov_b32 m0, s20
	s_nop 0
	global_load_lds_dwordx4 v[142:143], off
	v_lshl_add_u64 v[142:143], s[16:17], 0, v[128:129]
	s_add_i32 m0, s20, 0x2000
	s_nop 0
	global_load_lds_dwordx4 v[142:143], off
	s_waitcnt vmcnt(6)
	s_barrier
	v_mfma_f32_16x16x32_bf16 v[52:55], v[198:201], v[166:169], v[52:55]
	v_mfma_f32_16x16x32_bf16 v[48:51], v[206:209], v[166:169], v[48:51]
	v_mfma_f32_16x16x32_bf16 v[36:39], v[198:201], v[174:177], v[36:39]
	v_mfma_f32_16x16x32_bf16 v[32:35], v[206:209], v[174:177], v[32:35]
	v_mfma_f32_16x16x32_bf16 v[20:23], v[198:201], v[182:185], v[20:23]
	v_mfma_f32_16x16x32_bf16 v[16:19], v[206:209], v[182:185], v[16:19]
	v_mfma_f32_16x16x32_bf16 v[4:7], v[198:201], v[190:193], v[4:7]
	v_mfma_f32_16x16x32_bf16 v[0:3], v[206:209], v[190:193], v[0:3]
	v_mfma_f32_16x16x32_bf16 v[52:55], v[202:205], v[170:173], v[52:55]
	v_mfma_f32_16x16x32_bf16 v[48:51], v[210:213], v[170:173], v[48:51]
	v_mfma_f32_16x16x32_bf16 v[36:39], v[202:205], v[178:181], v[36:39]
	v_mfma_f32_16x16x32_bf16 v[32:35], v[210:213], v[178:181], v[32:35]
	v_mfma_f32_16x16x32_bf16 v[20:23], v[202:205], v[186:189], v[20:23]
	v_mfma_f32_16x16x32_bf16 v[16:19], v[210:213], v[186:189], v[16:19]
	v_mfma_f32_16x16x32_bf16 v[4:7], v[202:205], v[194:197], v[4:7]
	v_mfma_f32_16x16x32_bf16 v[0:3], v[210:213], v[194:197], v[0:3]
	s_add_i32 s49, s49, 2
	s_add_u32 s47, s47, 0x100
	s_addc_u32 s48, s48, 0
	s_cmp_gt_u32 s49, 13
	s_mov_b64 s[16:17], s[18:19]
	s_barrier
	s_cbranch_scc0 .LBB0_145
	s_mov_b32 s98, 0xbfb8aa3b
	v_pk_mul_f32 v[142:143], v[124:125], s[98:99] op_sel_hi:[1,0]
	v_exp_f32_e32 v142, v142
	v_exp_f32_e32 v143, v143
	s_lshl_b32 s16, s40, 8
	v_add_f32_e32 v142, 1.0, v142
	v_rcp_f32_e32 v150, v142
	v_add_f32_e32 v142, 1.0, v143
	v_rcp_f32_e32 v151, v142
	s_mov_b32 s17, s9
	v_lshl_add_u32 v149, s41, 8, v144
	v_lshl_add_u64 v[142:143], v[132:133], 0, s[16:17]
	v_pk_mul_f32 v[124:125], v[124:125], v[150:151]
	v_pk_mul_f32 v[150:151], v[126:127], s[98:99] op_sel_hi:[1,0]
	v_exp_f32_e32 v150, v150
	v_exp_f32_e32 v151, v151
	v_pk_mul_f32 v[116:117], v[124:125], v[116:117]
	s_and_b64 vcc, exec, s[2:3]
	v_pk_add_f32 v[124:125], v[150:151], 1.0 op_sel_hi:[1,0]
	v_pk_mul_f32 v[150:151], v[120:121], s[98:99] op_sel_hi:[1,0]
	v_rcp_f32_e32 v124, v124
	v_rcp_f32_e32 v125, v125
	v_exp_f32_e32 v150, v150
	v_exp_f32_e32 v151, v151
	s_mov_b32 s41, s8
	v_pk_mul_f32 v[124:125], v[126:127], v[124:125]
	v_pk_add_f32 v[126:127], v[150:151], 1.0 op_sel_hi:[1,0]
	v_pk_mul_f32 v[150:151], v[122:123], s[98:99] op_sel_hi:[1,0]
	v_exp_f32_e32 v150, v150
	v_exp_f32_e32 v151, v151
	v_rcp_f32_e32 v126, v126
	v_rcp_f32_e32 v127, v127
	v_pk_add_f32 v[150:151], v[150:151], 1.0 op_sel_hi:[1,0]
	v_rcp_f32_e32 v150, v150
	v_rcp_f32_e32 v151, v151
	v_pk_mul_f32 v[120:121], v[120:121], v[126:127]
	v_pk_mul_f32 v[118:119], v[124:125], v[118:119]
	v_pk_mul_f32 v[120:121], v[120:121], v[112:113]
	v_pk_mul_f32 v[112:113], v[122:123], v[150:151]
	s_mov_b32 s40, s10
	v_pk_mul_f32 v[122:123], v[112:113], v[114:115]
	v_mul_f32_e32 v115, 0xbfb8aa3b, v108
	v_cvt_pk_bf16_f32 v112, v116, v117
	v_exp_f32_e32 v116, v115
	v_mul_f32_e32 v115, 0xbfb8aa3b, v109
	v_exp_f32_e32 v117, v115
	v_cvt_pk_bf16_f32 v113, v118, v119
	v_cvt_pk_bf16_f32 v114, v120, v121
	v_cvt_pk_bf16_f32 v115, v122, v123
	v_pk_add_f32 v[116:117], v[116:117], 1.0 op_sel_hi:[1,0]
	v_mad_i64_i32 v[118:119], s[16:17], v149, s38, v[142:143]
	v_rcp_f32_e32 v116, v116
	v_rcp_f32_e32 v117, v117
	global_store_dwordx4 v[118:119], v[112:115], off
	s_mov_b64 s[18:19], s[14:15]
	v_pk_mul_f32 v[108:109], v[108:109], v[116:117]
	v_pk_mul_f32 v[112:113], v[110:111], s[98:99] op_sel_hi:[1,0]
	v_exp_f32_e32 v112, v112
	v_exp_f32_e32 v113, v113
	v_pk_mul_f32 v[100:101], v[108:109], v[100:101]
	v_or_b32_e32 v114, 16, v149
	v_pk_add_f32 v[108:109], v[112:113], 1.0 op_sel_hi:[1,0]
	v_pk_mul_f32 v[112:113], v[104:105], s[98:99] op_sel_hi:[1,0]
	v_rcp_f32_e32 v108, v108
	v_rcp_f32_e32 v109, v109
	v_exp_f32_e32 v112, v112
	v_exp_f32_e32 v113, v113
	v_pk_mul_f32 v[108:109], v[110:111], v[108:109]
	v_pk_add_f32 v[110:111], v[112:113], 1.0 op_sel_hi:[1,0]
	v_pk_mul_f32 v[112:113], v[106:107], s[98:99] op_sel_hi:[1,0]
	v_exp_f32_e32 v112, v112
	v_exp_f32_e32 v113, v113
	v_rcp_f32_e32 v110, v110
	v_rcp_f32_e32 v111, v111
	v_pk_add_f32 v[112:113], v[112:113], 1.0 op_sel_hi:[1,0]
	v_rcp_f32_e32 v112, v112
; __device__ __forceinline__ void gemm_phase(const bf16_t* __restrict__ A, const bf16_t* __restrict__ Bt, bf16_t* __restrict__ C, int M, int N, int K,
;                                            int ldc, const int EPI, char* smem, const int wid_u) {
;     ...
;             float o[8];
; #pragma unroll
;             for (int n = 0; n < 2; ++n) {
;               const f32x4 a = acc[ai][0][m][n], b = acc[ai][1][m][n];
; #pragma unroll
;               for (int j = 0; j < 4; ++j) o[n * 4 + j] = a[j] * __builtin_amdgcn_rcpf(1.f + __expf(-a[j])) * b[j];
;             }
;             *(uint4*)(C + row * ldc + (bcol >> 1) + wc * 32 + fq * 8) = pack8(o);
	v_rcp_f32_e32 v113, v113
	v_pk_mul_f32 v[104:105], v[104:105], v[110:111]
	v_pk_mul_f32 v[102:103], v[108:109], v[102:103]
	v_pk_mul_f32 v[104:105], v[104:105], v[96:97]
	v_pk_mul_f32 v[96:97], v[106:107], v[112:113]
	s_nop 0
	v_pk_mul_f32 v[106:107], v[96:97], v[98:99]
	v_mul_f32_e32 v99, 0xbfb8aa3b, v92
	v_cvt_pk_bf16_f32 v96, v100, v101
	v_exp_f32_e32 v100, v99
	v_mul_f32_e32 v99, 0xbfb8aa3b, v93
	v_exp_f32_e32 v101, v99
	v_cvt_pk_bf16_f32 v97, v102, v103
	v_cvt_pk_bf16_f32 v98, v104, v105
	v_cvt_pk_bf16_f32 v99, v106, v107
	v_pk_add_f32 v[100:101], v[100:101], 1.0 op_sel_hi:[1,0]
	v_mad_i64_i32 v[102:103], s[16:17], v114, s38, v[142:143]
	v_rcp_f32_e32 v100, v100
	v_rcp_f32_e32 v101, v101
	global_store_dwordx4 v[102:103], v[96:99], off
	v_pk_mul_f32 v[92:93], v[92:93], v[100:101]
	s_nop 0
	v_pk_mul_f32 v[96:97], v[94:95], s[98:99] op_sel_hi:[1,0]
	v_exp_f32_e32 v96, v96
	v_exp_f32_e32 v97, v97
	v_pk_mul_f32 v[84:85], v[92:93], v[84:85]
	v_or_b32_e32 v98, 32, v149
	v_pk_add_f32 v[92:93], v[96:97], 1.0 op_sel_hi:[1,0]
	v_pk_mul_f32 v[96:97], v[88:89], s[98:99] op_sel_hi:[1,0]
	v_rcp_f32_e32 v92, v92
	v_rcp_f32_e32 v93, v93
	v_exp_f32_e32 v96, v96
	v_exp_f32_e32 v97, v97
	v_pk_mul_f32 v[92:93], v[94:95], v[92:93]
	v_pk_add_f32 v[94:95], v[96:97], 1.0 op_sel_hi:[1,0]
	v_pk_mul_f32 v[96:97], v[90:91], s[98:99] op_sel_hi:[1,0]
	v_exp_f32_e32 v96, v96
	v_exp_f32_e32 v97, v97
	v_rcp_f32_e32 v94, v94
	v_rcp_f32_e32 v95, v95
	v_pk_add_f32 v[96:97], v[96:97], 1.0 op_sel_hi:[1,0]
	v_rcp_f32_e32 v96, v96
	v_rcp_f32_e32 v97, v97
	v_pk_mul_f32 v[88:89], v[88:89], v[94:95]
	v_pk_mul_f32 v[86:87], v[92:93], v[86:87]
	v_pk_mul_f32 v[88:89], v[88:89], v[80:81]
	v_pk_mul_f32 v[80:81], v[90:91], v[96:97]
	s_nop 0
	v_pk_mul_f32 v[90:91], v[80:81], v[82:83]
	v_mul_f32_e32 v83, 0xbfb8aa3b, v76
	v_cvt_pk_bf16_f32 v80, v84, v85
	v_exp_f32_e32 v84, v83
	v_mul_f32_e32 v83, 0xbfb8aa3b, v77
	v_exp_f32_e32 v85, v83
	v_cvt_pk_bf16_f32 v81, v86, v87
	v_cvt_pk_bf16_f32 v82, v88, v89
	v_cvt_pk_bf16_f32 v83, v90, v91
	v_pk_add_f32 v[84:85], v[84:85], 1.0 op_sel_hi:[1,0]
	v_mad_i64_i32 v[86:87], s[16:17], v98, s38, v[142:143]
	v_rcp_f32_e32 v84, v84
	v_rcp_f32_e32 v85, v85
	global_store_dwordx4 v[86:87], v[80:83], off
	v_pk_mul_f32 v[76:77], v[76:77], v[84:85]
	s_nop 0
	v_pk_mul_f32 v[80:81], v[78:79], s[98:99] op_sel_hi:[1,0]
	v_exp_f32_e32 v80, v80
	v_exp_f32_e32 v81, v81
	v_pk_mul_f32 v[68:69], v[76:77], v[68:69]
	v_or_b32_e32 v82, 48, v149
	v_pk_add_f32 v[76:77], v[80:81], 1.0 op_sel_hi:[1,0]
	v_pk_mul_f32 v[80:81], v[72:73], s[98:99] op_sel_hi:[1,0]
	v_rcp_f32_e32 v76, v76
	v_rcp_f32_e32 v77, v77
	v_exp_f32_e32 v80, v80
	v_exp_f32_e32 v81, v81
	v_pk_mul_f32 v[76:77], v[78:79], v[76:77]
	v_pk_add_f32 v[78:79], v[80:81], 1.0 op_sel_hi:[1,0]
	v_pk_mul_f32 v[80:81], v[74:75], s[98:99] op_sel_hi:[1,0]
	v_exp_f32_e32 v80, v80
	v_exp_f32_e32 v81, v81
	v_rcp_f32_e32 v78, v78
	v_rcp_f32_e32 v79, v79
	v_pk_add_f32 v[80:81], v[80:81], 1.0 op_sel_hi:[1,0]
	v_rcp_f32_e32 v80, v80
	v_rcp_f32_e32 v81, v81
	v_pk_mul_f32 v[72:73], v[72:73], v[78:79]
	v_pk_mul_f32 v[70:71], v[76:77], v[70:71]
	v_pk_mul_f32 v[72:73], v[72:73], v[64:65]
	v_pk_mul_f32 v[64:65], v[74:75], v[80:81]
	s_nop 0
	v_pk_mul_f32 v[74:75], v[64:65], v[66:67]
	v_mul_f32_e32 v67, 0xbfb8aa3b, v60
	v_cvt_pk_bf16_f32 v64, v68, v69
	v_exp_f32_e32 v68, v67
	v_mul_f32_e32 v67, 0xbfb8aa3b, v61
	v_exp_f32_e32 v69, v67
	v_cvt_pk_bf16_f32 v65, v70, v71
	v_cvt_pk_bf16_f32 v66, v72, v73
	v_cvt_pk_bf16_f32 v67, v74, v75
	v_pk_add_f32 v[68:69], v[68:69], 1.0 op_sel_hi:[1,0]
	v_mad_i64_i32 v[70:71], s[16:17], v82, s38, v[142:143]
	v_rcp_f32_e32 v68, v68
	v_rcp_f32_e32 v69, v69
	global_store_dwordx4 v[70:71], v[64:67], off
	v_pk_mul_f32 v[60:61], v[60:61], v[68:69]
	s_nop 0
	v_pk_mul_f32 v[64:65], v[62:63], s[98:99] op_sel_hi:[1,0]
	v_exp_f32_e32 v64, v64
	v_exp_f32_e32 v65, v65
	v_pk_mul_f32 v[52:53], v[60:61], v[52:53]
	v_add_u32_e32 v66, 0x80, v149
	v_pk_add_f32 v[60:61], v[64:65], 1.0 op_sel_hi:[1,0]
	v_pk_mul_f32 v[64:65], v[56:57], s[98:99] op_sel_hi:[1,0]
	v_rcp_f32_e32 v60, v60
	v_rcp_f32_e32 v61, v61
	v_exp_f32_e32 v64, v64
	v_exp_f32_e32 v65, v65
	v_pk_mul_f32 v[60:61], v[62:63], v[60:61]
	v_pk_add_f32 v[62:63], v[64:65], 1.0 op_sel_hi:[1,0]
	v_pk_mul_f32 v[64:65], v[58:59], s[98:99] op_sel_hi:[1,0]
	v_exp_f32_e32 v64, v64
	v_exp_f32_e32 v65, v65
	v_rcp_f32_e32 v62, v62
	v_rcp_f32_e32 v63, v63
	v_pk_add_f32 v[64:65], v[64:65], 1.0 op_sel_hi:[1,0]
	v_rcp_f32_e32 v64, v64
	v_rcp_f32_e32 v65, v65
	v_pk_mul_f32 v[56:57], v[56:57], v[62:63]
	v_pk_mul_f32 v[54:55], v[60:61], v[54:55]
	v_pk_mul_f32 v[56:57], v[56:57], v[48:49]
	v_pk_mul_f32 v[48:49], v[58:59], v[64:65]
	s_nop 0
	v_pk_mul_f32 v[58:59], v[48:49], v[50:51]
	v_mul_f32_e32 v51, 0xbfb8aa3b, v44
; #define WAIT_V(n) asm volatile("s_waitcnt vmcnt(" #n ")" ::: "memory")
; #define BAR __builtin_amdgcn_s_barrier()
; __device__ __forceinline__ void gemm_phase(const bf16_t* __restrict__ A, const bf16_t* __restrict__ Bt, bf16_t* __restrict__ C, int M, int N, int K,
;                                            int ldc, const int EPI, char* smem, const int wid_u) {
;     ...
;             float o[8];
; #pragma unroll
;             for (int n = 0; n < 2; ++n) {
;               const f32x4 a = acc[ai][0][m][n], b = acc[ai][1][m][n];
; #pragma unroll
;               for (int j = 0; j < 4; ++j) o[n * 4 + j] = a[j] * __builtin_amdgcn_rcpf(1.f + __expf(-a[j])) * b[j];
;             }
;             *(uint4*)(C + row * ldc + (bcol >> 1) + wc * 32 + fq * 8) = pack8(o);
;     ...
;     if (!has_next) break;
; #pragma unroll
;     for (int a = 0; a < 2; ++a)
; #pragma unroll
;       for (int b = 0; b < 2; ++b)
; #pragma unroll
;         for (int m = 0; m < 4; ++m)
; #pragma unroll
;           for (int n = 0; n < 2; ++n) acc[a][b][m][n] = (f32x4){0.f, 0.f, 0.f, 0.f};
;     pm = npm; pn = npn; cA = nA; cB = nB; ++ui;
;   }
;   WAIT_V(0);
;   if (wr == 0) BAR;
;   BAR;
	v_cvt_pk_bf16_f32 v48, v52, v53
	v_exp_f32_e32 v52, v51
	v_mul_f32_e32 v51, 0xbfb8aa3b, v45
	v_exp_f32_e32 v53, v51
	v_cvt_pk_bf16_f32 v49, v54, v55
	v_cvt_pk_bf16_f32 v50, v56, v57
	v_cvt_pk_bf16_f32 v51, v58, v59
	v_pk_add_f32 v[52:53], v[52:53], 1.0 op_sel_hi:[1,0]
	v_mad_i64_i32 v[54:55], s[16:17], v66, s38, v[142:143]
	v_rcp_f32_e32 v52, v52
	v_rcp_f32_e32 v53, v53
	global_store_dwordx4 v[54:55], v[48:51], off
	v_pk_mul_f32 v[44:45], v[44:45], v[52:53]
	s_nop 0
	v_pk_mul_f32 v[48:49], v[46:47], s[98:99] op_sel_hi:[1,0]
	v_exp_f32_e32 v48, v48
	v_exp_f32_e32 v49, v49
	v_pk_mul_f32 v[36:37], v[44:45], v[36:37]
	v_add_u32_e32 v50, 0x90, v149
	v_pk_add_f32 v[44:45], v[48:49], 1.0 op_sel_hi:[1,0]
	v_pk_mul_f32 v[48:49], v[40:41], s[98:99] op_sel_hi:[1,0]
	v_rcp_f32_e32 v44, v44
	v_rcp_f32_e32 v45, v45
	v_exp_f32_e32 v48, v48
	v_exp_f32_e32 v49, v49
	v_pk_mul_f32 v[44:45], v[46:47], v[44:45]
	v_pk_add_f32 v[46:47], v[48:49], 1.0 op_sel_hi:[1,0]
	v_pk_mul_f32 v[48:49], v[42:43], s[98:99] op_sel_hi:[1,0]
	v_exp_f32_e32 v48, v48
	v_exp_f32_e32 v49, v49
	v_rcp_f32_e32 v46, v46
	v_rcp_f32_e32 v47, v47
	v_pk_add_f32 v[48:49], v[48:49], 1.0 op_sel_hi:[1,0]
	v_rcp_f32_e32 v48, v48
	v_rcp_f32_e32 v49, v49
	v_pk_mul_f32 v[40:41], v[40:41], v[46:47]
	v_pk_mul_f32 v[38:39], v[44:45], v[38:39]
	v_pk_mul_f32 v[40:41], v[40:41], v[32:33]
	v_pk_mul_f32 v[32:33], v[42:43], v[48:49]
	s_nop 0
	v_pk_mul_f32 v[42:43], v[32:33], v[34:35]
	v_mul_f32_e32 v35, 0xbfb8aa3b, v28
	v_cvt_pk_bf16_f32 v32, v36, v37
	v_exp_f32_e32 v36, v35
	v_mul_f32_e32 v35, 0xbfb8aa3b, v29
	v_exp_f32_e32 v37, v35
	v_cvt_pk_bf16_f32 v33, v38, v39
	v_cvt_pk_bf16_f32 v34, v40, v41
	v_cvt_pk_bf16_f32 v35, v42, v43
	v_pk_add_f32 v[36:37], v[36:37], 1.0 op_sel_hi:[1,0]
	v_mad_i64_i32 v[38:39], s[16:17], v50, s38, v[142:143]
	v_rcp_f32_e32 v36, v36
	v_rcp_f32_e32 v37, v37
	global_store_dwordx4 v[38:39], v[32:35], off
	v_pk_mul_f32 v[28:29], v[28:29], v[36:37]
	s_nop 0
	v_pk_mul_f32 v[32:33], v[30:31], s[98:99] op_sel_hi:[1,0]
	v_exp_f32_e32 v32, v32
	v_exp_f32_e32 v33, v33
	v_pk_mul_f32 v[20:21], v[28:29], v[20:21]
	v_add_u32_e32 v34, 0xa0, v149
	v_pk_add_f32 v[28:29], v[32:33], 1.0 op_sel_hi:[1,0]
	v_pk_mul_f32 v[32:33], v[24:25], s[98:99] op_sel_hi:[1,0]
	v_rcp_f32_e32 v28, v28
	v_rcp_f32_e32 v29, v29
	v_exp_f32_e32 v32, v32
	v_exp_f32_e32 v33, v33
	v_pk_mul_f32 v[28:29], v[30:31], v[28:29]
	v_pk_add_f32 v[30:31], v[32:33], 1.0 op_sel_hi:[1,0]
	v_pk_mul_f32 v[32:33], v[26:27], s[98:99] op_sel_hi:[1,0]
	v_exp_f32_e32 v32, v32
	v_exp_f32_e32 v33, v33
	v_rcp_f32_e32 v30, v30
	v_rcp_f32_e32 v31, v31
	v_pk_add_f32 v[32:33], v[32:33], 1.0 op_sel_hi:[1,0]
	v_rcp_f32_e32 v32, v32
	v_rcp_f32_e32 v33, v33
	v_pk_mul_f32 v[24:25], v[24:25], v[30:31]
	v_pk_mul_f32 v[22:23], v[28:29], v[22:23]
	v_pk_mul_f32 v[24:25], v[24:25], v[16:17]
	v_pk_mul_f32 v[16:17], v[26:27], v[32:33]
	s_nop 0
	v_pk_mul_f32 v[26:27], v[16:17], v[18:19]
	v_mul_f32_e32 v19, 0xbfb8aa3b, v12
	v_cvt_pk_bf16_f32 v16, v20, v21
	v_exp_f32_e32 v20, v19
	v_mul_f32_e32 v19, 0xbfb8aa3b, v13
	v_exp_f32_e32 v21, v19
	v_cvt_pk_bf16_f32 v17, v22, v23
	v_cvt_pk_bf16_f32 v18, v24, v25
	v_cvt_pk_bf16_f32 v19, v26, v27
	v_pk_add_f32 v[20:21], v[20:21], 1.0 op_sel_hi:[1,0]
	v_mad_i64_i32 v[22:23], s[16:17], v34, s38, v[142:143]
	v_rcp_f32_e32 v20, v20
	v_rcp_f32_e32 v21, v21
	global_store_dwordx4 v[22:23], v[16:19], off
	v_pk_mul_f32 v[12:13], v[12:13], v[20:21]
	s_nop 0
	v_pk_mul_f32 v[16:17], v[14:15], s[98:99] op_sel_hi:[1,0]
	v_exp_f32_e32 v16, v16
	v_exp_f32_e32 v17, v17
	v_pk_mul_f32 v[4:5], v[12:13], v[4:5]
	v_add_u32_e32 v18, 0xb0, v149
	v_pk_add_f32 v[12:13], v[16:17], 1.0 op_sel_hi:[1,0]
	v_pk_mul_f32 v[16:17], v[8:9], s[98:99] op_sel_hi:[1,0]
	v_rcp_f32_e32 v12, v12
	v_rcp_f32_e32 v13, v13
	v_exp_f32_e32 v16, v16
	v_exp_f32_e32 v17, v17
	v_pk_mul_f32 v[12:13], v[14:15], v[12:13]
	v_pk_add_f32 v[14:15], v[16:17], 1.0 op_sel_hi:[1,0]
	v_pk_mul_f32 v[16:17], v[10:11], s[98:99] op_sel_hi:[1,0]
	v_exp_f32_e32 v16, v16
	v_exp_f32_e32 v17, v17
	v_rcp_f32_e32 v14, v14
	v_rcp_f32_e32 v15, v15
	v_pk_add_f32 v[16:17], v[16:17], 1.0 op_sel_hi:[1,0]
	v_rcp_f32_e32 v16, v16
	v_rcp_f32_e32 v17, v17
	v_pk_mul_f32 v[8:9], v[8:9], v[14:15]
	v_pk_mul_f32 v[6:7], v[12:13], v[6:7]
	v_pk_mul_f32 v[8:9], v[8:9], v[0:1]
	v_pk_mul_f32 v[0:1], v[10:11], v[16:17]
	s_nop 0
	v_pk_mul_f32 v[10:11], v[0:1], v[2:3]
	v_cvt_pk_bf16_f32 v0, v4, v5
	v_mad_i64_i32 v[4:5], s[16:17], v18, s38, v[142:143]
	v_cvt_pk_bf16_f32 v1, v6, v7
	v_cvt_pk_bf16_f32 v2, v8, v9
	v_cvt_pk_bf16_f32 v3, v10, v11
	s_mov_b64 s[16:17], s[12:13]
	global_store_dwordx4 v[4:5], v[0:3], off
	s_cbranch_vccz .LBB0_142
	s_waitcnt vmcnt(0)
	s_cmpk_gt_u32 s24, 0xff
	s_cbranch_scc1 .LBB0_149
	s_barrier

; #define STG(P, GB) do { const char* _gb = (GB); \
;     _Pragma("unroll") for (int _i = 0; _i < 2; ++_i) { \
;       __builtin_amdgcn_global_load_lds((const unsigned*)(_gb + voff[_i]), \
;         (LAS unsigned*)((LAS char*)(P) + ldsw + _i * 8192), 16, 0, 0); } } while (0)
; #define LDA(dst, b, h) _Pragma("unroll") for (int m = 0; m < 4; ++m) _Pragma("unroll") for (int k = 0; k < 2; ++k) \
;     dst[m][k] = *(const LAS bf16x8*)((LAS char*)SA(b, h) + aoff + m * 2048 + k * 1024)
; #define LDB(dst, b, h) _Pragma("unroll") for (int n = 0; n < 2; ++n) _Pragma("unroll") for (int k = 0; k < 2; ++k) \
;     dst[n][k] = *(const LAS bf16x8*)((LAS char*)SB(b, h) + boff + n * 2048 + k * 1024)
; #define MMA(ai, bj, At_, Bt_) do { __builtin_amdgcn_s_setprio(1); \
;     _Pragma("unroll") for (int m = 0; m < 4; ++m) _Pragma("unroll") for (int n = 0; n < 2; ++n) _Pragma("unroll") for (int k = 0; k < 2; ++k) \
;       acc[ai][bj][m][n] = __builtin_amdgcn_mfma_f32_16x16x32_bf16(Bt_[n][k], At_[m][k], acc[ai][bj][m][n], 0, 0, 0); \
;     __builtin_amdgcn_s_setprio(0); } while (0)
; #define WAIT_V(n) asm volatile("s_waitcnt vmcnt(" #n ")" ::: "memory")
; #define WAIT_L(n) asm volatile("s_waitcnt lgkmcnt(" #n ")" ::: "memory")
; #define BAR __builtin_amdgcn_s_barrier()
; #define SCHED __builtin_amdgcn_sched_barrier(0)
; __device__ __forceinline__ void gemm_phase(const bf16_t* __restrict__ A, const bf16_t* __restrict__ Bt, bf16_t* __restrict__ C, int M, int N, int K,
;                                            int ldc, const int EPI, char* smem, const int wid_u) {
;     ...
;       LDB(B0, 0, 0); SCHED; LDA(At, 0, 0); STG(SA(1, 1), a1 + hstep);
;       WAIT_L(8); BAR; WAIT_L(0); MMA(0, 0, At, B0); BAR; SCHED;
;       LDB(B1, 0, 1); STG(SB(0, 0), b2);
;       BAR; WAIT_L(0); MMA(0, 1, At, B1); BAR;
;       LDA(At, 0, 1); STG(SA(0, 0), a2);
;       BAR; WAIT_L(0); MMA(1, 0, At, B0); BAR; SCHED;
;       STG(SB(0, 1), b2 + hstep);
;       WAIT_V(6); BAR; MMA(1, 1, At, B1); BAR;
;       LDB(B0, 1, 0); SCHED; LDA(At, 1, 0); STG(SA(0, 1), a2 + hstep);
;       WAIT_L(8); BAR; WAIT_L(0); MMA(0, 0, At, B0); BAR; SCHED;
.LBB0_1026:
	ds_read_b128 v[150:153], v146
	ds_read_b128 v[154:157], v146 offset:1024
	ds_read_b128 v[158:161], v146 offset:2048
	ds_read_b128 v[162:165], v146 offset:3072
	s_add_u32 s20, s18, 0x100
	s_addc_u32 s21, s19, 0
	s_cmp_eq_u32 s53, 12
	s_cselect_b32 s25, s48, s21
	s_cselect_b32 s24, s49, s20
	s_cselect_b32 s23, s13, s52
	s_cselect_b32 s22, s50, s51
	v_lshl_add_u64 v[142:143], s[18:19], 0, v[136:137]
	s_add_i32 m0, s34, 0xc000
	ds_read_b128 v[166:169], v147
	ds_read_b128 v[170:173], v147 offset:1024
	ds_read_b128 v[174:177], v147 offset:2048
	ds_read_b128 v[178:181], v147 offset:3072
	ds_read_b128 v[182:185], v147 offset:4096
	ds_read_b128 v[186:189], v147 offset:5120
	ds_read_b128 v[190:193], v147 offset:6144
	ds_read_b128 v[194:197], v147 offset:7168
	global_load_lds_dwordx4 v[142:143], off
	v_lshl_add_u64 v[142:143], s[18:19], 0, v[134:135]
	s_add_i32 m0, s34, 0xe000
	s_nop 0
	global_load_lds_dwordx4 v[142:143], off
	s_waitcnt lgkmcnt(8)
	s_barrier
	s_waitcnt lgkmcnt(0)
	s_waitcnt lgkmcnt(0)
	v_mfma_f32_16x16x32_bf16 v[124:127], v[150:153], v[166:169], v[124:127]
	v_mfma_f32_16x16x32_bf16 v[120:123], v[158:161], v[166:169], v[120:123]
	v_mfma_f32_16x16x32_bf16 v[108:111], v[150:153], v[174:177], v[108:111]
	v_mfma_f32_16x16x32_bf16 v[104:107], v[158:161], v[174:177], v[104:107]
	v_mfma_f32_16x16x32_bf16 v[92:95], v[150:153], v[182:185], v[92:95]
	v_mfma_f32_16x16x32_bf16 v[88:91], v[158:161], v[182:185], v[88:91]
	v_mfma_f32_16x16x32_bf16 v[76:79], v[150:153], v[190:193], v[76:79]
	v_mfma_f32_16x16x32_bf16 v[72:75], v[158:161], v[190:193], v[72:75]
	v_mfma_f32_16x16x32_bf16 v[124:127], v[154:157], v[170:173], v[124:127]
	v_mfma_f32_16x16x32_bf16 v[120:123], v[162:165], v[170:173], v[120:123]
	v_mfma_f32_16x16x32_bf16 v[108:111], v[154:157], v[178:181], v[108:111]
	v_mfma_f32_16x16x32_bf16 v[104:107], v[162:165], v[178:181], v[104:107]
	v_mfma_f32_16x16x32_bf16 v[92:95], v[154:157], v[186:189], v[92:95]
	v_mfma_f32_16x16x32_bf16 v[88:91], v[162:165], v[186:189], v[88:91]
	v_mfma_f32_16x16x32_bf16 v[76:79], v[154:157], v[194:197], v[76:79]
	v_mfma_f32_16x16x32_bf16 v[72:75], v[162:165], v[194:197], v[72:75]
	s_barrier
	s_add_i32 s18, s40, s31
	v_lshl_add_u64 v[142:143], s[22:23], 0, v[130:131]
	s_mov_b32 m0, s18
	ds_read_b128 v[198:201], v148
	ds_read_b128 v[202:205], v148 offset:1024
	ds_read_b128 v[206:209], v148 offset:2048
	ds_read_b128 v[210:213], v148 offset:3072
	global_load_lds_dwordx4 v[142:143], off
	v_lshl_add_u64 v[214:215], s[22:23], 0, v[128:129]
	s_add_i32 m0, s18, 0x2000
	s_nop 0
	global_load_lds_dwordx4 v[214:215], off
	s_barrier
	s_waitcnt lgkmcnt(0)
	s_waitcnt lgkmcnt(0)
	v_mfma_f32_16x16x32_bf16 v[116:119], v[198:201], v[166:169], v[116:119]
	v_mfma_f32_16x16x32_bf16 v[112:115], v[206:209], v[166:169], v[112:115]
	v_mfma_f32_16x16x32_bf16 v[100:103], v[198:201], v[174:177], v[100:103]
	v_mfma_f32_16x16x32_bf16 v[96:99], v[206:209], v[174:177], v[96:99]
	v_mfma_f32_16x16x32_bf16 v[84:87], v[198:201], v[182:185], v[84:87]
	v_mfma_f32_16x16x32_bf16 v[80:83], v[206:209], v[182:185], v[80:83]
	v_mfma_f32_16x16x32_bf16 v[68:71], v[198:201], v[190:193], v[68:71]
	v_mfma_f32_16x16x32_bf16 v[64:67], v[206:209], v[190:193], v[64:67]
	v_mfma_f32_16x16x32_bf16 v[116:119], v[202:205], v[170:173], v[116:119]
	v_mfma_f32_16x16x32_bf16 v[112:115], v[210:213], v[170:173], v[112:115]
	v_mfma_f32_16x16x32_bf16 v[100:103], v[202:205], v[178:181], v[100:103]
	v_mfma_f32_16x16x32_bf16 v[96:99], v[210:213], v[178:181], v[96:99]
	v_mfma_f32_16x16x32_bf16 v[84:87], v[202:205], v[186:189], v[84:87]
	v_mfma_f32_16x16x32_bf16 v[80:83], v[210:213], v[186:189], v[80:83]
	v_mfma_f32_16x16x32_bf16 v[68:71], v[202:205], v[194:197], v[68:71]
	v_mfma_f32_16x16x32_bf16 v[64:67], v[210:213], v[194:197], v[64:67]
	s_mov_b32 m0, s34
	v_lshl_add_u64 v[216:217], s[24:25], 0, v[130:131]
	s_barrier
	ds_read_b128 v[166:169], v147 offset:16384
	ds_read_b128 v[170:173], v147 offset:17408
	ds_read_b128 v[174:177], v147 offset:18432
	ds_read_b128 v[178:181], v147 offset:19456
	ds_read_b128 v[182:185], v147 offset:20480
	ds_read_b128 v[186:189], v147 offset:21504
	ds_read_b128 v[190:193], v147 offset:22528
	ds_read_b128 v[194:197], v147 offset:23552
	global_load_lds_dwordx4 v[216:217], off
	v_lshl_add_u64 v[218:219], s[24:25], 0, v[128:129]
	s_mov_b32 m0, s35
	s_nop 0
	global_load_lds_dwordx4 v[218:219], off
	s_barrier
	s_waitcnt lgkmcnt(0)
	s_waitcnt lgkmcnt(0)
	v_mfma_f32_16x16x32_bf16 v[60:63], v[150:153], v[166:169], v[60:63]
	v_mfma_f32_16x16x32_bf16 v[56:59], v[158:161], v[166:169], v[56:59]
	v_mfma_f32_16x16x32_bf16 v[44:47], v[150:153], v[174:177], v[44:47]
	v_mfma_f32_16x16x32_bf16 v[40:43], v[158:161], v[174:177], v[40:43]
	v_mfma_f32_16x16x32_bf16 v[28:31], v[150:153], v[182:185], v[28:31]
	v_mfma_f32_16x16x32_bf16 v[24:27], v[158:161], v[182:185], v[24:27]
	v_mfma_f32_16x16x32_bf16 v[12:15], v[150:153], v[190:193], v[12:15]
	v_mfma_f32_16x16x32_bf16 v[8:11], v[158:161], v[190:193], v[8:11]
	v_mfma_f32_16x16x32_bf16 v[60:63], v[154:157], v[170:173], v[60:63]
	v_mfma_f32_16x16x32_bf16 v[56:59], v[162:165], v[170:173], v[56:59]
	v_mfma_f32_16x16x32_bf16 v[44:47], v[154:157], v[178:181], v[44:47]
	v_mfma_f32_16x16x32_bf16 v[40:43], v[162:165], v[178:181], v[40:43]
	v_mfma_f32_16x16x32_bf16 v[28:31], v[154:157], v[186:189], v[28:31]
	v_mfma_f32_16x16x32_bf16 v[24:27], v[162:165], v[186:189], v[24:27]
	v_mfma_f32_16x16x32_bf16 v[12:15], v[154:157], v[194:197], v[12:15]
	v_mfma_f32_16x16x32_bf16 v[8:11], v[162:165], v[194:197], v[8:11]
	s_barrier
; #define STG(P, GB) do { const char* _gb = (GB); \
;     _Pragma("unroll") for (int _i = 0; _i < 2; ++_i) { \
;       __builtin_amdgcn_global_load_lds((const unsigned*)(_gb + voff[_i]), \
;         (LAS unsigned*)((LAS char*)(P) + ldsw + _i * 8192), 16, 0, 0); } } while (0)
; #define LDA(dst, b, h) _Pragma("unroll") for (int m = 0; m < 4; ++m) _Pragma("unroll") for (int k = 0; k < 2; ++k) \
;     dst[m][k] = *(const LAS bf16x8*)((LAS char*)SA(b, h) + aoff + m * 2048 + k * 1024)
; #define LDB(dst, b, h) _Pragma("unroll") for (int n = 0; n < 2; ++n) _Pragma("unroll") for (int k = 0; k < 2; ++k) \
;     dst[n][k] = *(const LAS bf16x8*)((LAS char*)SB(b, h) + boff + n * 2048 + k * 1024)
; #define MMA(ai, bj, At_, Bt_) do { __builtin_amdgcn_s_setprio(1); \
;     _Pragma("unroll") for (int m = 0; m < 4; ++m) _Pragma("unroll") for (int n = 0; n < 2; ++n) _Pragma("unroll") for (int k = 0; k < 2; ++k) \
;       acc[ai][bj][m][n] = __builtin_amdgcn_mfma_f32_16x16x32_bf16(Bt_[n][k], At_[m][k], acc[ai][bj][m][n], 0, 0, 0); \
;     __builtin_amdgcn_s_setprio(0); } while (0)
; #define WAIT_V(n) asm volatile("s_waitcnt vmcnt(" #n ")" ::: "memory")
; #define WAIT_L(n) asm volatile("s_waitcnt lgkmcnt(" #n ")" ::: "memory")
; #define BAR __builtin_amdgcn_s_barrier()
; #define SCHED __builtin_amdgcn_sched_barrier(0)
; __device__ __forceinline__ void gemm_phase(const bf16_t* __restrict__ A, const bf16_t* __restrict__ Bt, bf16_t* __restrict__ C, int M, int N, int K,
;                                            int ldc, const int EPI, char* smem, const int wid_u) {
;     ...
;       WAIT_V(6); BAR; MMA(1, 1, At, B1); BAR;
;       LDB(B0, 1, 0); SCHED; LDA(At, 1, 0); STG(SA(0, 1), a2 + hstep);
;       WAIT_L(8); BAR; WAIT_L(0); MMA(0, 0, At, B0); BAR; SCHED;
;       LDB(B1, 1, 1); STG(SB(1, 0), b3);
;       BAR; WAIT_L(0); MMA(0, 1, At, B1); BAR;
;       LDA(At, 1, 1); STG(SA(1, 0), a3);
	s_add_u32 s18, s22, 0x40000
	s_addc_u32 s19, s23, 0
	s_add_i32 s54, s41, s31
	v_lshl_add_u64 v[150:151], s[18:19], 0, v[130:131]
	s_mov_b32 m0, s54
	s_nop 0
	global_load_lds_dwordx4 v[150:151], off
	v_lshl_add_u64 v[150:151], s[18:19], 0, v[128:129]
	s_add_i32 m0, s54, 0x2000
	s_nop 0
	global_load_lds_dwordx4 v[150:151], off
	s_waitcnt vmcnt(6)
	s_barrier
	v_mfma_f32_16x16x32_bf16 v[52:55], v[198:201], v[166:169], v[52:55]
	v_mfma_f32_16x16x32_bf16 v[48:51], v[206:209], v[166:169], v[48:51]
	v_mfma_f32_16x16x32_bf16 v[36:39], v[198:201], v[174:177], v[36:39]
	v_mfma_f32_16x16x32_bf16 v[32:35], v[206:209], v[174:177], v[32:35]
	v_mfma_f32_16x16x32_bf16 v[20:23], v[198:201], v[182:185], v[20:23]
	v_mfma_f32_16x16x32_bf16 v[16:19], v[206:209], v[182:185], v[16:19]
	v_mfma_f32_16x16x32_bf16 v[4:7], v[198:201], v[190:193], v[4:7]
	v_mfma_f32_16x16x32_bf16 v[0:3], v[206:209], v[190:193], v[0:3]
	v_mfma_f32_16x16x32_bf16 v[52:55], v[202:205], v[170:173], v[52:55]
	v_mfma_f32_16x16x32_bf16 v[48:51], v[210:213], v[170:173], v[48:51]
	v_mfma_f32_16x16x32_bf16 v[36:39], v[202:205], v[178:181], v[36:39]
	v_mfma_f32_16x16x32_bf16 v[32:35], v[210:213], v[178:181], v[32:35]
	v_mfma_f32_16x16x32_bf16 v[20:23], v[202:205], v[186:189], v[20:23]
	v_mfma_f32_16x16x32_bf16 v[16:19], v[210:213], v[186:189], v[16:19]
	v_mfma_f32_16x16x32_bf16 v[4:7], v[202:205], v[194:197], v[4:7]
	v_mfma_f32_16x16x32_bf16 v[0:3], v[210:213], v[194:197], v[0:3]
	s_add_i32 s54, 0, 0x18000
	v_add_u32_e32 v149, s54, v145
	s_barrier
	ds_read_b128 v[150:153], v149
	ds_read_b128 v[154:157], v149 offset:1024
	ds_read_b128 v[158:161], v149 offset:2048
	ds_read_b128 v[162:165], v149 offset:3072
	s_add_u32 s18, s24, 0x40000
	s_addc_u32 s19, s25, 0
	s_mov_b32 m0, s36
	v_lshl_add_u64 v[198:199], s[18:19], 0, v[130:131]
	ds_read_b128 v[166:169], v147 offset:32768
	ds_read_b128 v[170:173], v147 offset:33792
	ds_read_b128 v[174:177], v147 offset:34816
	ds_read_b128 v[178:181], v147 offset:35840
	ds_read_b128 v[182:185], v147 offset:36864
	ds_read_b128 v[186:189], v147 offset:37888
	ds_read_b128 v[190:193], v147 offset:38912
	ds_read_b128 v[194:197], v147 offset:39936
	global_load_lds_dwordx4 v[198:199], off
	v_lshl_add_u64 v[198:199], s[18:19], 0, v[128:129]
	s_mov_b32 m0, s37
	s_nop 0
	global_load_lds_dwordx4 v[198:199], off
	s_waitcnt lgkmcnt(8)
	s_barrier
	s_waitcnt lgkmcnt(0)
	s_waitcnt lgkmcnt(0)
	v_mfma_f32_16x16x32_bf16 v[124:127], v[150:153], v[166:169], v[124:127]
	v_mfma_f32_16x16x32_bf16 v[120:123], v[158:161], v[166:169], v[120:123]
	v_mfma_f32_16x16x32_bf16 v[108:111], v[150:153], v[174:177], v[108:111]
	v_mfma_f32_16x16x32_bf16 v[104:107], v[158:161], v[174:177], v[104:107]
	v_mfma_f32_16x16x32_bf16 v[92:95], v[150:153], v[182:185], v[92:95]
	v_mfma_f32_16x16x32_bf16 v[88:91], v[158:161], v[182:185], v[88:91]
	v_mfma_f32_16x16x32_bf16 v[76:79], v[150:153], v[190:193], v[76:79]
	v_mfma_f32_16x16x32_bf16 v[72:75], v[158:161], v[190:193], v[72:75]
	v_mfma_f32_16x16x32_bf16 v[124:127], v[154:157], v[170:173], v[124:127]
	v_mfma_f32_16x16x32_bf16 v[120:123], v[162:165], v[170:173], v[120:123]
	v_mfma_f32_16x16x32_bf16 v[108:111], v[154:157], v[178:181], v[108:111]
	v_mfma_f32_16x16x32_bf16 v[104:107], v[162:165], v[178:181], v[104:107]
	v_mfma_f32_16x16x32_bf16 v[92:95], v[154:157], v[186:189], v[92:95]
	v_mfma_f32_16x16x32_bf16 v[88:91], v[162:165], v[186:189], v[88:91]
	v_mfma_f32_16x16x32_bf16 v[76:79], v[154:157], v[194:197], v[76:79]
	v_mfma_f32_16x16x32_bf16 v[72:75], v[162:165], v[194:197], v[72:75]
	s_barrier
	s_add_i32 s24, 0, 0x1c000
	s_add_i32 s18, s54, s31
	v_add_u32_e32 v149, s24, v145
	v_lshl_add_u64 v[142:143], v[142:143], 0, s[10:11]
	s_mov_b32 m0, s18
	ds_read_b128 v[198:201], v149
	ds_read_b128 v[202:205], v149 offset:1024
	ds_read_b128 v[206:209], v149 offset:2048
	ds_read_b128 v[210:213], v149 offset:3072
	global_load_lds_dwordx4 v[142:143], off
	v_lshl_add_u64 v[142:143], v[214:215], 0, s[10:11]
	s_add_i32 m0, s18, 0x2000
	s_nop 0
	global_load_lds_dwordx4 v[142:143], off
	s_barrier
	s_waitcnt lgkmcnt(0)
	s_waitcnt lgkmcnt(0)
	v_mfma_f32_16x16x32_bf16 v[116:119], v[198:201], v[166:169], v[116:119]
	v_mfma_f32_16x16x32_bf16 v[112:115], v[206:209], v[166:169], v[112:115]
	v_mfma_f32_16x16x32_bf16 v[100:103], v[198:201], v[174:177], v[100:103]
	v_mfma_f32_16x16x32_bf16 v[96:99], v[206:209], v[174:177], v[96:99]
	v_mfma_f32_16x16x32_bf16 v[84:87], v[198:201], v[182:185], v[84:87]
	v_mfma_f32_16x16x32_bf16 v[80:83], v[206:209], v[182:185], v[80:83]
	v_mfma_f32_16x16x32_bf16 v[68:71], v[198:201], v[190:193], v[68:71]
	v_mfma_f32_16x16x32_bf16 v[64:67], v[206:209], v[190:193], v[64:67]
	v_mfma_f32_16x16x32_bf16 v[116:119], v[202:205], v[170:173], v[116:119]
	v_mfma_f32_16x16x32_bf16 v[112:115], v[210:213], v[170:173], v[112:115]
	v_mfma_f32_16x16x32_bf16 v[100:103], v[202:205], v[178:181], v[100:103]
	v_mfma_f32_16x16x32_bf16 v[96:99], v[210:213], v[178:181], v[96:99]
	v_mfma_f32_16x16x32_bf16 v[84:87], v[202:205], v[186:189], v[84:87]
	v_mfma_f32_16x16x32_bf16 v[80:83], v[210:213], v[186:189], v[80:83]
	v_mfma_f32_16x16x32_bf16 v[68:71], v[202:205], v[194:197], v[68:71]
	v_mfma_f32_16x16x32_bf16 v[64:67], v[210:213], v[194:197], v[64:67]
	s_mov_b32 m0, s38
	v_lshl_add_u64 v[142:143], v[216:217], 0, s[10:11]
	s_barrier
	ds_read_b128 v[166:169], v147 offset:49152
	ds_read_b128 v[170:173], v147 offset:50176
	ds_read_b128 v[174:177], v147 offset:51200
	ds_read_b128 v[178:181], v147 offset:52224
	ds_read_b128 v[182:185], v147 offset:53248
	ds_read_b128 v[186:189], v147 offset:54272
	ds_read_b128 v[190:193], v147 offset:55296
	ds_read_b128 v[194:197], v147 offset:56320
	global_load_lds_dwordx4 v[142:143], off
	v_lshl_add_u64 v[142:143], v[218:219], 0, s[10:11]
	s_mov_b32 m0, s39
	s_nop 0
	global_load_lds_dwordx4 v[142:143], off
	s_barrier
; #define STG(P, GB) do { const char* _gb = (GB); \
;     _Pragma("unroll") for (int _i = 0; _i < 2; ++_i) { \
;       __builtin_amdgcn_global_load_lds((const unsigned*)(_gb + voff[_i]), \
;         (LAS unsigned*)((LAS char*)(P) + ldsw + _i * 8192), 16, 0, 0); } } while (0)
; #define MMA(ai, bj, At_, Bt_) do { __builtin_amdgcn_s_setprio(1); \
;     _Pragma("unroll") for (int m = 0; m < 4; ++m) _Pragma("unroll") for (int n = 0; n < 2; ++n) _Pragma("unroll") for (int k = 0; k < 2; ++k) \
;       acc[ai][bj][m][n] = __builtin_amdgcn_mfma_f32_16x16x32_bf16(Bt_[n][k], At_[m][k], acc[ai][bj][m][n], 0, 0, 0); \
;     __builtin_amdgcn_s_setprio(0); } while (0)
; #define WAIT_V(n) asm volatile("s_waitcnt vmcnt(" #n ")" ::: "memory")
; #define WAIT_L(n) asm volatile("s_waitcnt lgkmcnt(" #n ")" ::: "memory")
; #define BAR __builtin_amdgcn_s_barrier()
; #define SCHED __builtin_amdgcn_sched_barrier(0)
; __device__ __forceinline__ void gemm_phase(const bf16_t* __restrict__ A, const bf16_t* __restrict__ Bt, bf16_t* __restrict__ C, int M, int N, int K,
;                                            int ldc, const int EPI, char* smem, const int wid_u) {
;     ...
;       BAR; WAIT_L(0); MMA(1, 0, At, B0); BAR; SCHED;
;       STG(SB(1, 1), b3 + hstep);
;       WAIT_V(6); BAR; MMA(1, 1, At, B1); BAR;
;     ...
;             float o[8];
; #pragma unroll
;             for (int n = 0; n < 2; ++n) {
;               const f32x4 a = acc[ai][0][m][n], b = acc[ai][1][m][n];
; #pragma unroll
;               for (int j = 0; j < 4; ++j) o[n * 4 + j] = a[j] * __builtin_amdgcn_rcpf(1.f + __expf(-a[j])) * b[j];
;             }
;             *(uint4*)(C + row * ldc + (bcol >> 1) + wc * 32 + fq * 8) = pack8(o);
	s_waitcnt lgkmcnt(0)
	s_waitcnt lgkmcnt(0)
	v_mfma_f32_16x16x32_bf16 v[60:63], v[150:153], v[166:169], v[60:63]
	v_mfma_f32_16x16x32_bf16 v[56:59], v[158:161], v[166:169], v[56:59]
	v_mfma_f32_16x16x32_bf16 v[44:47], v[150:153], v[174:177], v[44:47]
	v_mfma_f32_16x16x32_bf16 v[40:43], v[158:161], v[174:177], v[40:43]
	v_mfma_f32_16x16x32_bf16 v[28:31], v[150:153], v[182:185], v[28:31]
	v_mfma_f32_16x16x32_bf16 v[24:27], v[158:161], v[182:185], v[24:27]
	v_mfma_f32_16x16x32_bf16 v[12:15], v[150:153], v[190:193], v[12:15]
	v_mfma_f32_16x16x32_bf16 v[8:11], v[158:161], v[190:193], v[8:11]
	v_mfma_f32_16x16x32_bf16 v[60:63], v[154:157], v[170:173], v[60:63]
	v_mfma_f32_16x16x32_bf16 v[56:59], v[162:165], v[170:173], v[56:59]
	v_mfma_f32_16x16x32_bf16 v[44:47], v[154:157], v[178:181], v[44:47]
	v_mfma_f32_16x16x32_bf16 v[40:43], v[162:165], v[178:181], v[40:43]
	v_mfma_f32_16x16x32_bf16 v[28:31], v[154:157], v[186:189], v[28:31]
	v_mfma_f32_16x16x32_bf16 v[24:27], v[162:165], v[186:189], v[24:27]
	v_mfma_f32_16x16x32_bf16 v[12:15], v[154:157], v[194:197], v[12:15]
	v_mfma_f32_16x16x32_bf16 v[8:11], v[162:165], v[194:197], v[8:11]
	s_barrier
	s_add_u32 s18, s22, 0x40080
	s_addc_u32 s19, s23, 0
	s_add_i32 s22, s24, s31
	v_lshl_add_u64 v[142:143], s[18:19], 0, v[130:131]
	s_mov_b32 m0, s22
	s_nop 0
	global_load_lds_dwordx4 v[142:143], off
	v_lshl_add_u64 v[142:143], s[18:19], 0, v[128:129]
	s_add_i32 m0, s22, 0x2000
	s_nop 0
	global_load_lds_dwordx4 v[142:143], off
	s_waitcnt vmcnt(6)
	s_barrier
	v_mfma_f32_16x16x32_bf16 v[52:55], v[198:201], v[166:169], v[52:55]
	v_mfma_f32_16x16x32_bf16 v[48:51], v[206:209], v[166:169], v[48:51]
	v_mfma_f32_16x16x32_bf16 v[36:39], v[198:201], v[174:177], v[36:39]
	v_mfma_f32_16x16x32_bf16 v[32:35], v[206:209], v[174:177], v[32:35]
	v_mfma_f32_16x16x32_bf16 v[20:23], v[198:201], v[182:185], v[20:23]
	v_mfma_f32_16x16x32_bf16 v[16:19], v[206:209], v[182:185], v[16:19]
	v_mfma_f32_16x16x32_bf16 v[4:7], v[198:201], v[190:193], v[4:7]
	v_mfma_f32_16x16x32_bf16 v[0:3], v[206:209], v[190:193], v[0:3]
	v_mfma_f32_16x16x32_bf16 v[52:55], v[202:205], v[170:173], v[52:55]
	v_mfma_f32_16x16x32_bf16 v[48:51], v[210:213], v[170:173], v[48:51]
	v_mfma_f32_16x16x32_bf16 v[36:39], v[202:205], v[178:181], v[36:39]
	v_mfma_f32_16x16x32_bf16 v[32:35], v[210:213], v[178:181], v[32:35]
	v_mfma_f32_16x16x32_bf16 v[20:23], v[202:205], v[186:189], v[20:23]
	v_mfma_f32_16x16x32_bf16 v[16:19], v[210:213], v[186:189], v[16:19]
	v_mfma_f32_16x16x32_bf16 v[4:7], v[202:205], v[194:197], v[4:7]
	v_mfma_f32_16x16x32_bf16 v[0:3], v[210:213], v[194:197], v[0:3]
	s_add_i32 s53, s53, 2
	s_add_u32 s51, s51, 0x100
	s_addc_u32 s52, s52, 0
	s_cmp_gt_u32 s53, 13
	s_mov_b64 s[18:19], s[20:21]
	s_barrier
	s_cbranch_scc0 .LBB0_1026
	s_mov_b32 s98, 0xbfb8aa3b
	v_pk_mul_f32 v[142:143], v[124:125], s[98:99] op_sel_hi:[1,0]
	v_exp_f32_e32 v142, v142
	v_exp_f32_e32 v143, v143
	s_lshl_b32 s18, s46, 8
	v_add_f32_e32 v142, 1.0, v142
	v_rcp_f32_e32 v150, v142
	v_add_f32_e32 v142, 1.0, v143
	v_rcp_f32_e32 v151, v142
	s_mov_b32 s19, s9
	v_lshl_add_u32 v149, s47, 8, v144
	v_lshl_add_u64 v[142:143], v[132:133], 0, s[18:19]
	v_pk_mul_f32 v[124:125], v[124:125], v[150:151]
	v_pk_mul_f32 v[150:151], v[126:127], s[98:99] op_sel_hi:[1,0]
	v_exp_f32_e32 v150, v150
	v_exp_f32_e32 v151, v151
	v_pk_mul_f32 v[116:117], v[124:125], v[116:117]
	s_and_b64 vcc, exec, s[4:5]
	v_pk_add_f32 v[124:125], v[150:151], 1.0 op_sel_hi:[1,0]
	v_pk_mul_f32 v[150:151], v[120:121], s[98:99] op_sel_hi:[1,0]
	v_rcp_f32_e32 v124, v124
	v_rcp_f32_e32 v125, v125
	v_exp_f32_e32 v150, v150
	v_exp_f32_e32 v151, v151
	s_mov_b32 s47, s8
	v_pk_mul_f32 v[124:125], v[126:127], v[124:125]
	v_pk_add_f32 v[126:127], v[150:151], 1.0 op_sel_hi:[1,0]
	v_pk_mul_f32 v[150:151], v[122:123], s[98:99] op_sel_hi:[1,0]
	v_exp_f32_e32 v150, v150
	v_exp_f32_e32 v151, v151
	v_rcp_f32_e32 v126, v126
	v_rcp_f32_e32 v127, v127
	v_pk_add_f32 v[150:151], v[150:151], 1.0 op_sel_hi:[1,0]
	v_rcp_f32_e32 v150, v150
	v_rcp_f32_e32 v151, v151
	v_pk_mul_f32 v[120:121], v[120:121], v[126:127]
	v_pk_mul_f32 v[118:119], v[124:125], v[118:119]
	v_pk_mul_f32 v[120:121], v[120:121], v[112:113]
	v_pk_mul_f32 v[112:113], v[122:123], v[150:151]
	s_mov_b32 s46, s12
	v_pk_mul_f32 v[122:123], v[112:113], v[114:115]
	v_mul_f32_e32 v115, 0xbfb8aa3b, v108
	v_cvt_pk_bf16_f32 v112, v116, v117
	v_exp_f32_e32 v116, v115
	v_mul_f32_e32 v115, 0xbfb8aa3b, v109
	v_exp_f32_e32 v117, v115
	v_cvt_pk_bf16_f32 v113, v118, v119
	v_cvt_pk_bf16_f32 v114, v120, v121
	v_cvt_pk_bf16_f32 v115, v122, v123
	v_pk_add_f32 v[116:117], v[116:117], 1.0 op_sel_hi:[1,0]
	v_mad_i64_i32 v[118:119], s[18:19], v149, s44, v[142:143]
	v_rcp_f32_e32 v116, v116
	v_rcp_f32_e32 v117, v117
	global_store_dwordx4 v[118:119], v[112:115], off
	s_mov_b64 s[20:21], s[16:17]
	v_pk_mul_f32 v[108:109], v[108:109], v[116:117]
	v_pk_mul_f32 v[112:113], v[110:111], s[98:99] op_sel_hi:[1,0]
	v_exp_f32_e32 v112, v112
	v_exp_f32_e32 v113, v113
	v_pk_mul_f32 v[100:101], v[108:109], v[100:101]
	v_or_b32_e32 v114, 16, v149
	v_pk_add_f32 v[108:109], v[112:113], 1.0 op_sel_hi:[1,0]
	v_pk_mul_f32 v[112:113], v[104:105], s[98:99] op_sel_hi:[1,0]
	v_rcp_f32_e32 v108, v108
	v_rcp_f32_e32 v109, v109
	v_exp_f32_e32 v112, v112
	v_exp_f32_e32 v113, v113
	v_pk_mul_f32 v[108:109], v[110:111], v[108:109]
	v_pk_add_f32 v[110:111], v[112:113], 1.0 op_sel_hi:[1,0]
	v_pk_mul_f32 v[112:113], v[106:107], s[98:99] op_sel_hi:[1,0]
	v_exp_f32_e32 v112, v112
	v_exp_f32_e32 v113, v113
	v_rcp_f32_e32 v110, v110
	v_rcp_f32_e32 v111, v111
	v_pk_add_f32 v[112:113], v[112:113], 1.0 op_sel_hi:[1,0]
	v_rcp_f32_e32 v112, v112
; __device__ __forceinline__ void gemm_phase(const bf16_t* __restrict__ A, const bf16_t* __restrict__ Bt, bf16_t* __restrict__ C, int M, int N, int K,
;                                            int ldc, const int EPI, char* smem, const int wid_u) {
;     ...
;             float o[8];
; #pragma unroll
;             for (int n = 0; n < 2; ++n) {
;               const f32x4 a = acc[ai][0][m][n], b = acc[ai][1][m][n];
; #pragma unroll
;               for (int j = 0; j < 4; ++j) o[n * 4 + j] = a[j] * __builtin_amdgcn_rcpf(1.f + __expf(-a[j])) * b[j];
;             }
;             *(uint4*)(C + row * ldc + (bcol >> 1) + wc * 32 + fq * 8) = pack8(o);
	v_rcp_f32_e32 v113, v113
	v_pk_mul_f32 v[104:105], v[104:105], v[110:111]
	v_pk_mul_f32 v[102:103], v[108:109], v[102:103]
	v_pk_mul_f32 v[104:105], v[104:105], v[96:97]
	v_pk_mul_f32 v[96:97], v[106:107], v[112:113]
	s_nop 0
	v_pk_mul_f32 v[106:107], v[96:97], v[98:99]
	v_mul_f32_e32 v99, 0xbfb8aa3b, v92
	v_cvt_pk_bf16_f32 v96, v100, v101
	v_exp_f32_e32 v100, v99
	v_mul_f32_e32 v99, 0xbfb8aa3b, v93
	v_exp_f32_e32 v101, v99
	v_cvt_pk_bf16_f32 v97, v102, v103
	v_cvt_pk_bf16_f32 v98, v104, v105
	v_cvt_pk_bf16_f32 v99, v106, v107
	v_pk_add_f32 v[100:101], v[100:101], 1.0 op_sel_hi:[1,0]
	v_mad_i64_i32 v[102:103], s[18:19], v114, s44, v[142:143]
	v_rcp_f32_e32 v100, v100
	v_rcp_f32_e32 v101, v101
	global_store_dwordx4 v[102:103], v[96:99], off
	v_pk_mul_f32 v[92:93], v[92:93], v[100:101]
	s_nop 0
	v_pk_mul_f32 v[96:97], v[94:95], s[98:99] op_sel_hi:[1,0]
	v_exp_f32_e32 v96, v96
	v_exp_f32_e32 v97, v97
	v_pk_mul_f32 v[84:85], v[92:93], v[84:85]
	v_or_b32_e32 v98, 32, v149
	v_pk_add_f32 v[92:93], v[96:97], 1.0 op_sel_hi:[1,0]
	v_pk_mul_f32 v[96:97], v[88:89], s[98:99] op_sel_hi:[1,0]
	v_rcp_f32_e32 v92, v92
	v_rcp_f32_e32 v93, v93
	v_exp_f32_e32 v96, v96
	v_exp_f32_e32 v97, v97
	v_pk_mul_f32 v[92:93], v[94:95], v[92:93]
	v_pk_add_f32 v[94:95], v[96:97], 1.0 op_sel_hi:[1,0]
	v_pk_mul_f32 v[96:97], v[90:91], s[98:99] op_sel_hi:[1,0]
	v_exp_f32_e32 v96, v96
	v_exp_f32_e32 v97, v97
	v_rcp_f32_e32 v94, v94
	v_rcp_f32_e32 v95, v95
	v_pk_add_f32 v[96:97], v[96:97], 1.0 op_sel_hi:[1,0]
	v_rcp_f32_e32 v96, v96
	v_rcp_f32_e32 v97, v97
	v_pk_mul_f32 v[88:89], v[88:89], v[94:95]
	v_pk_mul_f32 v[86:87], v[92:93], v[86:87]
	v_pk_mul_f32 v[88:89], v[88:89], v[80:81]
	v_pk_mul_f32 v[80:81], v[90:91], v[96:97]
	s_nop 0
	v_pk_mul_f32 v[90:91], v[80:81], v[82:83]
	v_mul_f32_e32 v83, 0xbfb8aa3b, v76
	v_cvt_pk_bf16_f32 v80, v84, v85
	v_exp_f32_e32 v84, v83
	v_mul_f32_e32 v83, 0xbfb8aa3b, v77
	v_exp_f32_e32 v85, v83
	v_cvt_pk_bf16_f32 v81, v86, v87
	v_cvt_pk_bf16_f32 v82, v88, v89
	v_cvt_pk_bf16_f32 v83, v90, v91
	v_pk_add_f32 v[84:85], v[84:85], 1.0 op_sel_hi:[1,0]
	v_mad_i64_i32 v[86:87], s[18:19], v98, s44, v[142:143]
	v_rcp_f32_e32 v84, v84
	v_rcp_f32_e32 v85, v85
	global_store_dwordx4 v[86:87], v[80:83], off
	v_pk_mul_f32 v[76:77], v[76:77], v[84:85]
	s_nop 0
	v_pk_mul_f32 v[80:81], v[78:79], s[98:99] op_sel_hi:[1,0]
	v_exp_f32_e32 v80, v80
	v_exp_f32_e32 v81, v81
	v_pk_mul_f32 v[68:69], v[76:77], v[68:69]
	v_or_b32_e32 v82, 48, v149
	v_pk_add_f32 v[76:77], v[80:81], 1.0 op_sel_hi:[1,0]
	v_pk_mul_f32 v[80:81], v[72:73], s[98:99] op_sel_hi:[1,0]
	v_rcp_f32_e32 v76, v76
	v_rcp_f32_e32 v77, v77
	v_exp_f32_e32 v80, v80
	v_exp_f32_e32 v81, v81
	v_pk_mul_f32 v[76:77], v[78:79], v[76:77]
	v_pk_add_f32 v[78:79], v[80:81], 1.0 op_sel_hi:[1,0]
	v_pk_mul_f32 v[80:81], v[74:75], s[98:99] op_sel_hi:[1,0]
	v_exp_f32_e32 v80, v80
	v_exp_f32_e32 v81, v81
	v_rcp_f32_e32 v78, v78
	v_rcp_f32_e32 v79, v79
	v_pk_add_f32 v[80:81], v[80:81], 1.0 op_sel_hi:[1,0]
	v_rcp_f32_e32 v80, v80
	v_rcp_f32_e32 v81, v81
	v_pk_mul_f32 v[72:73], v[72:73], v[78:79]
	v_pk_mul_f32 v[70:71], v[76:77], v[70:71]
	v_pk_mul_f32 v[72:73], v[72:73], v[64:65]
	v_pk_mul_f32 v[64:65], v[74:75], v[80:81]
	s_nop 0
	v_pk_mul_f32 v[74:75], v[64:65], v[66:67]
	v_mul_f32_e32 v67, 0xbfb8aa3b, v60
	v_cvt_pk_bf16_f32 v64, v68, v69
	v_exp_f32_e32 v68, v67
	v_mul_f32_e32 v67, 0xbfb8aa3b, v61
	v_exp_f32_e32 v69, v67
	v_cvt_pk_bf16_f32 v65, v70, v71
	v_cvt_pk_bf16_f32 v66, v72, v73
	v_cvt_pk_bf16_f32 v67, v74, v75
	v_pk_add_f32 v[68:69], v[68:69], 1.0 op_sel_hi:[1,0]
	v_mad_i64_i32 v[70:71], s[18:19], v82, s44, v[142:143]
	v_rcp_f32_e32 v68, v68
	v_rcp_f32_e32 v69, v69
	global_store_dwordx4 v[70:71], v[64:67], off
	v_pk_mul_f32 v[60:61], v[60:61], v[68:69]
	s_nop 0
	v_pk_mul_f32 v[64:65], v[62:63], s[98:99] op_sel_hi:[1,0]
	v_exp_f32_e32 v64, v64
	v_exp_f32_e32 v65, v65
	v_pk_mul_f32 v[52:53], v[60:61], v[52:53]
	v_add_u32_e32 v66, 0x80, v149
	v_pk_add_f32 v[60:61], v[64:65], 1.0 op_sel_hi:[1,0]
	v_pk_mul_f32 v[64:65], v[56:57], s[98:99] op_sel_hi:[1,0]
	v_rcp_f32_e32 v60, v60
	v_rcp_f32_e32 v61, v61
	v_exp_f32_e32 v64, v64
	v_exp_f32_e32 v65, v65
	v_pk_mul_f32 v[60:61], v[62:63], v[60:61]
	v_pk_add_f32 v[62:63], v[64:65], 1.0 op_sel_hi:[1,0]
	v_pk_mul_f32 v[64:65], v[58:59], s[98:99] op_sel_hi:[1,0]
	v_exp_f32_e32 v64, v64
	v_exp_f32_e32 v65, v65
	v_rcp_f32_e32 v62, v62
	v_rcp_f32_e32 v63, v63
	v_pk_add_f32 v[64:65], v[64:65], 1.0 op_sel_hi:[1,0]
	v_rcp_f32_e32 v64, v64
	v_rcp_f32_e32 v65, v65
	v_pk_mul_f32 v[56:57], v[56:57], v[62:63]
	v_pk_mul_f32 v[54:55], v[60:61], v[54:55]
	v_pk_mul_f32 v[56:57], v[56:57], v[48:49]
	v_pk_mul_f32 v[48:49], v[58:59], v[64:65]
	s_nop 0
	v_pk_mul_f32 v[58:59], v[48:49], v[50:51]
	v_mul_f32_e32 v51, 0xbfb8aa3b, v44
; #define WAIT_V(n) asm volatile("s_waitcnt vmcnt(" #n ")" ::: "memory")
; #define BAR __builtin_amdgcn_s_barrier()
; __device__ __forceinline__ void gemm_phase(const bf16_t* __restrict__ A, const bf16_t* __restrict__ Bt, bf16_t* __restrict__ C, int M, int N, int K,
;                                            int ldc, const int EPI, char* smem, const int wid_u) {
;     ...
;             float o[8];
; #pragma unroll
;             for (int n = 0; n < 2; ++n) {
;               const f32x4 a = acc[ai][0][m][n], b = acc[ai][1][m][n];
; #pragma unroll
;               for (int j = 0; j < 4; ++j) o[n * 4 + j] = a[j] * __builtin_amdgcn_rcpf(1.f + __expf(-a[j])) * b[j];
;             }
;             *(uint4*)(C + row * ldc + (bcol >> 1) + wc * 32 + fq * 8) = pack8(o);
;     ...
;     if (!has_next) break;
; #pragma unroll
;     for (int a = 0; a < 2; ++a)
; #pragma unroll
;       for (int b = 0; b < 2; ++b)
; #pragma unroll
;         for (int m = 0; m < 4; ++m)
; #pragma unroll
;           for (int n = 0; n < 2; ++n) acc[a][b][m][n] = (f32x4){0.f, 0.f, 0.f, 0.f};
;     pm = npm; pn = npn; cA = nA; cB = nB; ++ui;
;   }
;   WAIT_V(0);
;   if (wr == 0) BAR;
;   BAR;
	v_cvt_pk_bf16_f32 v48, v52, v53
	v_exp_f32_e32 v52, v51
	v_mul_f32_e32 v51, 0xbfb8aa3b, v45
	v_exp_f32_e32 v53, v51
	v_cvt_pk_bf16_f32 v49, v54, v55
	v_cvt_pk_bf16_f32 v50, v56, v57
	v_cvt_pk_bf16_f32 v51, v58, v59
	v_pk_add_f32 v[52:53], v[52:53], 1.0 op_sel_hi:[1,0]
	v_mad_i64_i32 v[54:55], s[18:19], v66, s44, v[142:143]
	v_rcp_f32_e32 v52, v52
	v_rcp_f32_e32 v53, v53
	global_store_dwordx4 v[54:55], v[48:51], off
	v_pk_mul_f32 v[44:45], v[44:45], v[52:53]
	s_nop 0
	v_pk_mul_f32 v[48:49], v[46:47], s[98:99] op_sel_hi:[1,0]
	v_exp_f32_e32 v48, v48
	v_exp_f32_e32 v49, v49
	v_pk_mul_f32 v[36:37], v[44:45], v[36:37]
	v_add_u32_e32 v50, 0x90, v149
	v_pk_add_f32 v[44:45], v[48:49], 1.0 op_sel_hi:[1,0]
	v_pk_mul_f32 v[48:49], v[40:41], s[98:99] op_sel_hi:[1,0]
	v_rcp_f32_e32 v44, v44
	v_rcp_f32_e32 v45, v45
	v_exp_f32_e32 v48, v48
	v_exp_f32_e32 v49, v49
	v_pk_mul_f32 v[44:45], v[46:47], v[44:45]
	v_pk_add_f32 v[46:47], v[48:49], 1.0 op_sel_hi:[1,0]
	v_pk_mul_f32 v[48:49], v[42:43], s[98:99] op_sel_hi:[1,0]
	v_exp_f32_e32 v48, v48
	v_exp_f32_e32 v49, v49
	v_rcp_f32_e32 v46, v46
	v_rcp_f32_e32 v47, v47
	v_pk_add_f32 v[48:49], v[48:49], 1.0 op_sel_hi:[1,0]
	v_rcp_f32_e32 v48, v48
	v_rcp_f32_e32 v49, v49
	v_pk_mul_f32 v[40:41], v[40:41], v[46:47]
	v_pk_mul_f32 v[38:39], v[44:45], v[38:39]
	v_pk_mul_f32 v[40:41], v[40:41], v[32:33]
	v_pk_mul_f32 v[32:33], v[42:43], v[48:49]
	s_nop 0
	v_pk_mul_f32 v[42:43], v[32:33], v[34:35]
	v_mul_f32_e32 v35, 0xbfb8aa3b, v28
	v_cvt_pk_bf16_f32 v32, v36, v37
	v_exp_f32_e32 v36, v35
	v_mul_f32_e32 v35, 0xbfb8aa3b, v29
	v_exp_f32_e32 v37, v35
	v_cvt_pk_bf16_f32 v33, v38, v39
	v_cvt_pk_bf16_f32 v34, v40, v41
	v_cvt_pk_bf16_f32 v35, v42, v43
	v_pk_add_f32 v[36:37], v[36:37], 1.0 op_sel_hi:[1,0]
	v_mad_i64_i32 v[38:39], s[18:19], v50, s44, v[142:143]
	v_rcp_f32_e32 v36, v36
	v_rcp_f32_e32 v37, v37
	global_store_dwordx4 v[38:39], v[32:35], off
	v_pk_mul_f32 v[28:29], v[28:29], v[36:37]
	s_nop 0
	v_pk_mul_f32 v[32:33], v[30:31], s[98:99] op_sel_hi:[1,0]
	v_exp_f32_e32 v32, v32
	v_exp_f32_e32 v33, v33
	v_pk_mul_f32 v[20:21], v[28:29], v[20:21]
	v_add_u32_e32 v34, 0xa0, v149
	v_pk_add_f32 v[28:29], v[32:33], 1.0 op_sel_hi:[1,0]
	v_pk_mul_f32 v[32:33], v[24:25], s[98:99] op_sel_hi:[1,0]
	v_rcp_f32_e32 v28, v28
	v_rcp_f32_e32 v29, v29
	v_exp_f32_e32 v32, v32
	v_exp_f32_e32 v33, v33
	v_pk_mul_f32 v[28:29], v[30:31], v[28:29]
	v_pk_add_f32 v[30:31], v[32:33], 1.0 op_sel_hi:[1,0]
	v_pk_mul_f32 v[32:33], v[26:27], s[98:99] op_sel_hi:[1,0]
	v_exp_f32_e32 v32, v32
	v_exp_f32_e32 v33, v33
	v_rcp_f32_e32 v30, v30
	v_rcp_f32_e32 v31, v31
	v_pk_add_f32 v[32:33], v[32:33], 1.0 op_sel_hi:[1,0]
	v_rcp_f32_e32 v32, v32
	v_rcp_f32_e32 v33, v33
	v_pk_mul_f32 v[24:25], v[24:25], v[30:31]
	v_pk_mul_f32 v[22:23], v[28:29], v[22:23]
	v_pk_mul_f32 v[24:25], v[24:25], v[16:17]
	v_pk_mul_f32 v[16:17], v[26:27], v[32:33]
	s_nop 0
	v_pk_mul_f32 v[26:27], v[16:17], v[18:19]
	v_mul_f32_e32 v19, 0xbfb8aa3b, v12
	v_cvt_pk_bf16_f32 v16, v20, v21
	v_exp_f32_e32 v20, v19
	v_mul_f32_e32 v19, 0xbfb8aa3b, v13
	v_exp_f32_e32 v21, v19
	v_cvt_pk_bf16_f32 v17, v22, v23
	v_cvt_pk_bf16_f32 v18, v24, v25
	v_cvt_pk_bf16_f32 v19, v26, v27
	v_pk_add_f32 v[20:21], v[20:21], 1.0 op_sel_hi:[1,0]
	v_mad_i64_i32 v[22:23], s[18:19], v34, s44, v[142:143]
	v_rcp_f32_e32 v20, v20
	v_rcp_f32_e32 v21, v21
	global_store_dwordx4 v[22:23], v[16:19], off
	v_pk_mul_f32 v[12:13], v[12:13], v[20:21]
	s_nop 0
	v_pk_mul_f32 v[16:17], v[14:15], s[98:99] op_sel_hi:[1,0]
	v_exp_f32_e32 v16, v16
	v_exp_f32_e32 v17, v17
	v_pk_mul_f32 v[4:5], v[12:13], v[4:5]
	v_add_u32_e32 v18, 0xb0, v149
	v_pk_add_f32 v[12:13], v[16:17], 1.0 op_sel_hi:[1,0]
	v_pk_mul_f32 v[16:17], v[8:9], s[98:99] op_sel_hi:[1,0]
	v_rcp_f32_e32 v12, v12
	v_rcp_f32_e32 v13, v13
	v_exp_f32_e32 v16, v16
	v_exp_f32_e32 v17, v17
	v_pk_mul_f32 v[12:13], v[14:15], v[12:13]
	v_pk_add_f32 v[14:15], v[16:17], 1.0 op_sel_hi:[1,0]
	v_pk_mul_f32 v[16:17], v[10:11], s[98:99] op_sel_hi:[1,0]
	v_exp_f32_e32 v16, v16
	v_exp_f32_e32 v17, v17
	v_rcp_f32_e32 v14, v14
	v_rcp_f32_e32 v15, v15
	v_pk_add_f32 v[16:17], v[16:17], 1.0 op_sel_hi:[1,0]
	v_rcp_f32_e32 v16, v16
	v_rcp_f32_e32 v17, v17
	v_pk_mul_f32 v[8:9], v[8:9], v[14:15]
	v_pk_mul_f32 v[6:7], v[12:13], v[6:7]
	v_pk_mul_f32 v[8:9], v[8:9], v[0:1]
	v_pk_mul_f32 v[0:1], v[10:11], v[16:17]
	s_nop 0
	v_pk_mul_f32 v[10:11], v[0:1], v[2:3]
	v_cvt_pk_bf16_f32 v0, v4, v5
	v_mad_i64_i32 v[4:5], s[18:19], v18, s44, v[142:143]
	v_cvt_pk_bf16_f32 v1, v6, v7
	v_cvt_pk_bf16_f32 v2, v8, v9
	v_cvt_pk_bf16_f32 v3, v10, v11
	s_mov_b64 s[18:19], s[14:15]
	global_store_dwordx4 v[4:5], v[0:3], off
	s_cbranch_vccz .LBB0_1023
	s_waitcnt vmcnt(0)
	s_cmpk_gt_u32 s26, 0xff
	s_cbranch_scc1 .LBB0_1030
	s_barrier

; #define LAS __attribute__((address_space(3)))
; __device__ __forceinline__ unsigned xb_add(unsigned* p, unsigned v) { return __hip_atomic_fetch_add(p, v, __ATOMIC_RELAXED, __HIP_MEMORY_SCOPE_AGENT); }
; __device__ __forceinline__ unsigned xb_xcc_id() { return (unsigned)__builtin_amdgcn_s_getreg((3 << 11) | 20) & 0xFu; }
; #define RUN_PHASE(PH) do { KP kp = kp0; asm volatile("" : "+s"(kp)); do_phase(*kp, PH, dyn_smem, wid_u); \
;     if (PH == 0) grid.sync(); \
;     else if (PH + 1 < NPHASE) xcd_barrier(*kp, (volatile LAS unsigned*)((LAS char*)dyn_smem + (SMEM_BYTES - 16)), wid_u); } while (0)
; __global__ void __launch_bounds__(NTHR, 2) mega_kernel(Params p) {
;   cg::grid_group grid = cg::this_grid();
;   const int wid_u = __builtin_amdgcn_readfirstlane(threadIdx.x >> 6);
;   typedef const __attribute__((address_space(4))) Params* KP;
;   const KP kp0 = (KP)__builtin_amdgcn_kernarg_segment_ptr();
;   volatile LAS unsigned* st = (volatile LAS unsigned*)((LAS char*)dyn_smem + (SMEM_BYTES - 16));
;   if (threadIdx.x < 2) st[threadIdx.x] = 0u;
;   __syncthreads();
;   if (threadIdx.x == 0) (void)xb_add(&((unsigned*)(kp0->ws + OFF_BAR))[XB_XCNT(xb_xcc_id())], 1u);
;     ...
;   RUN_PHASE(0); RUN_PHASE(1); RUN_PHASE(2); RUN_PHASE(3); RUN_PHASE(4); RUN_PHASE(5); RUN_PHASE(6);
;   RUN_PHASE(7); RUN_PHASE(8); RUN_PHASE(9); RUN_PHASE(10); RUN_PHASE(11); RUN_PHASE(12); RUN_PHASE(13);
;     ...
; }
	.amdhsa_kernel _Z11mega_kernel6Params
		.amdhsa_group_segment_fixed_size 0
		.amdhsa_private_segment_fixed_size 0
		.amdhsa_kernarg_size 536
		.amdhsa_user_sgpr_count 2
		.amdhsa_user_sgpr_dispatch_ptr 0
		.amdhsa_user_sgpr_queue_ptr 0
		.amdhsa_user_sgpr_kernarg_segment_ptr 1
		.amdhsa_user_sgpr_dispatch_id 0
		.amdhsa_user_sgpr_kernarg_preload_length 0
		.amdhsa_user_sgpr_kernarg_preload_offset 0
		.amdhsa_user_sgpr_private_segment_size 0
		.amdhsa_uses_dynamic_stack 0
		.amdhsa_enable_private_segment 0
		.amdhsa_system_sgpr_workgroup_id_x 1
		.amdhsa_system_sgpr_workgroup_id_y 0
		.amdhsa_system_sgpr_workgroup_id_z 0
		.amdhsa_system_sgpr_workgroup_info 0
		.amdhsa_system_vgpr_workitem_id 2
		.amdhsa_next_free_vgpr 256
		.amdhsa_next_free_sgpr 100
		.amdhsa_accum_offset 256
		.amdhsa_reserve_vcc 1
		.amdhsa_float_round_mode_32 0
		.amdhsa_float_round_mode_16_64 0
		.amdhsa_float_denorm_mode_32 3
		.amdhsa_float_denorm_mode_16_64 3
		.amdhsa_dx10_clamp 1
		.amdhsa_ieee_mode 1
		.amdhsa_fp16_overflow 0
		.amdhsa_tg_split 0
		.amdhsa_exception_fp_ieee_invalid_op 0
		.amdhsa_exception_fp_denorm_src 0
		.amdhsa_exception_fp_ieee_div_zero 0
		.amdhsa_exception_fp_ieee_overflow 0
		.amdhsa_exception_fp_ieee_underflow 0
		.amdhsa_exception_fp_ieee_inexact 0
		.amdhsa_exception_int_div_zero 0
	.end_amdhsa_kernel

; #define LAS __attribute__((address_space(3)))
; __device__ __forceinline__ unsigned xb_add(unsigned* p, unsigned v) { return __hip_atomic_fetch_add(p, v, __ATOMIC_RELAXED, __HIP_MEMORY_SCOPE_AGENT); }
; __device__ __forceinline__ unsigned xb_xcc_id() { return (unsigned)__builtin_amdgcn_s_getreg((3 << 11) | 20) & 0xFu; }
; #define RUN_PHASE(PH) do { KP kp = kp0; asm volatile("" : "+s"(kp)); do_phase(*kp, PH, dyn_smem, wid_u); \
;     if (PH == 0) grid.sync(); \
;     else if (PH + 1 < NPHASE) xcd_barrier(*kp, (volatile LAS unsigned*)((LAS char*)dyn_smem + (SMEM_BYTES - 16)), wid_u); } while (0)
; __global__ void __launch_bounds__(NTHR, 2) mega_kernel(Params p) {
;   cg::grid_group grid = cg::this_grid();
;   const int wid_u = __builtin_amdgcn_readfirstlane(threadIdx.x >> 6);
;   typedef const __attribute__((address_space(4))) Params* KP;
;   const KP kp0 = (KP)__builtin_amdgcn_kernarg_segment_ptr();
;   volatile LAS unsigned* st = (volatile LAS unsigned*)((LAS char*)dyn_smem + (SMEM_BYTES - 16));
;   if (threadIdx.x < 2) st[threadIdx.x] = 0u;
;   __syncthreads();
;   if (threadIdx.x == 0) (void)xb_add(&((unsigned*)(kp0->ws + OFF_BAR))[XB_XCNT(xb_xcc_id())], 1u);
;     ...
;   RUN_PHASE(0); RUN_PHASE(1); RUN_PHASE(2); RUN_PHASE(3); RUN_PHASE(4); RUN_PHASE(5); RUN_PHASE(6);
;   RUN_PHASE(7); RUN_PHASE(8); RUN_PHASE(9); RUN_PHASE(10); RUN_PHASE(11); RUN_PHASE(12); RUN_PHASE(13);
;     ...
; }
; __global__ void __launch_bounds__(NTHR, 2) phase_kernel(Params p, int ph) {
;   const int wid_u = __builtin_amdgcn_readfirstlane(threadIdx.x >> 6);
;   do_phase(*(const __attribute__((address_space(4))) Params*)__builtin_amdgcn_kernarg_segment_ptr(), ph, dyn_smem, wid_u);
; }
amdhsa.kernels:
  - .agpr_count:     0
    .args:
      - .offset:         0
        .size:           280
        .value_kind:     by_value
      - .offset:         280
        .size:           4
        .value_kind:     hidden_block_count_x
      - .offset:         284
        .size:           4
        .value_kind:     hidden_block_count_y
      - .offset:         288
        .size:           4
        .value_kind:     hidden_block_count_z
      - .offset:         292
        .size:           2
        .value_kind:     hidden_group_size_x
      - .offset:         294
        .size:           2
        .value_kind:     hidden_group_size_y
      - .offset:         296
        .size:           2
        .value_kind:     hidden_group_size_z
      - .offset:         298
        .size:           2
        .value_kind:     hidden_remainder_x
      - .offset:         300
        .size:           2
        .value_kind:     hidden_remainder_y
      - .offset:         302
        .size:           2
        .value_kind:     hidden_remainder_z
      - .offset:         320
        .size:           8
        .value_kind:     hidden_global_offset_x
      - .offset:         328
        .size:           8
        .value_kind:     hidden_global_offset_y
      - .offset:         336
        .size:           8
        .value_kind:     hidden_global_offset_z
      - .offset:         344
        .size:           2
        .value_kind:     hidden_grid_dims
      - .offset:         368
        .size:           8
        .value_kind:     hidden_multigrid_sync_arg
      - .offset:         400
        .size:           4
        .value_kind:     hidden_dynamic_lds_size
    .group_segment_fixed_size: 0
    .kernarg_segment_align: 8
    .kernarg_segment_size: 536
    .language:       OpenCL C
    .language_version:
      - 2
      - 0
    .max_flat_workgroup_size: 512
    .name:           _Z11mega_kernel6Params
    .private_segment_fixed_size: 0
    .sgpr_count:     106
    .sgpr_spill_count: 7
    .symbol:         _Z11mega_kernel6Params.kd
    .uniform_work_group_size: 1
    .uses_dynamic_stack: false
    .vgpr_count:     256
    .vgpr_spill_count: 0
    .wavefront_size: 64
  - .agpr_count:     0
    .args:
      - .offset:         0
        .size:           280
        .value_kind:     by_value
      - .offset:         280
        .size:           4
        .value_kind:     by_value
      - .offset:         288
        .size:           4
        .value_kind:     hidden_block_count_x
      - .offset:         292
        .size:           4
        .value_kind:     hidden_block_count_y
      - .offset:         296
        .size:           4
        .value_kind:     hidden_block_count_z
      - .offset:         300
        .size:           2
        .value_kind:     hidden_group_size_x
      - .offset:         302
        .size:           2
        .value_kind:     hidden_group_size_y
      - .offset:         304
        .size:           2
        .value_kind:     hidden_group_size_z
      - .offset:         306
        .size:           2
        .value_kind:     hidden_remainder_x
      - .offset:         308
        .size:           2
        .value_kind:     hidden_remainder_y
      - .offset:         310
        .size:           2
        .value_kind:     hidden_remainder_z
      - .offset:         328
        .size:           8
        .value_kind:     hidden_global_offset_x
      - .offset:         336
        .size:           8
        .value_kind:     hidden_global_offset_y
      - .offset:         344
        .size:           8
        .value_kind:     hidden_global_offset_z
      - .offset:         352
        .size:           2
        .value_kind:     hidden_grid_dims
      - .offset:         408
        .size:           4
        .value_kind:     hidden_dynamic_lds_size
    .group_segment_fixed_size: 0
    .kernarg_segment_align: 8
    .kernarg_segment_size: 544
    .language:       OpenCL C
    .language_version:
      - 2
      - 0
    .max_flat_workgroup_size: 512
    .name:           _Z12phase_kernel6Paramsi
    .private_segment_fixed_size: 0
    .sgpr_count:     106
    .sgpr_spill_count: 0
    .symbol:         _Z12phase_kernel6Paramsi.kd
    .uniform_work_group_size: 1
    .uses_dynamic_stack: false
    .vgpr_count:     254
    .vgpr_spill_count: 0
    .wavefront_size: 64
